# attention epilogues: serialized ds_bpermute+masked-branch store chains replaced by DPP lane swap, batched converts and saddr stores (MLA, fox); DPP in diff
# speedup vs baseline: 1.0025x; 1.0025x over previous
; __device__ __forceinline__ unsigned cvtpk(float lo, float hi) { const cvt_f32x2 v = {lo, hi}; const cvt_bf16x2 r = __builtin_convertvector(v, cvt_bf16x2); return __builtin_bit_cast(unsigned, r); }
; __device__ __forceinline__ int crow(int r, int hi) { return (r & 3) + 8 * (r >> 2) + 4 * hi; }
; template <int MODE, int VARI>
; __device__ __forceinline__ void attn_unit(LAS unsigned char* lds, const int tid, const AttnP& a, float c2, float lam, const float* subln, float outscale, float fox_u, const bool fast) {
;     ...
;     } else if (WIDE) {
;         if (hi == 0) li_l[r32] = l_reg;
;         asm volatile("s_waitcnt lgkmcnt(0)" ::: "memory");
; #pragma unroll
;         for (int r = 0; r < 16; ++r) { const float rl = __builtin_amdgcn_rcpf(li_l[crow(r, hi)]);
; #pragma unroll
;             for (int d = 0; d < 4; ++d) o[d][r] *= rl; }
;     ...
;     if (WIDE || wid < 4) {
;         bf16_t* Ow = a.O + (size_t)qpos0 * 2048;
; #pragma unroll
;         for (int r = 0; r < 16; ++r) { const int orow = crow(r, hi);
; #pragma unroll
;             for (int d = 0; d < 4; ++d) { const float v = o[d][r]; const float vn = __shfl_xor(v, 1);
;                 if ((r32 & 1) == 0) *(unsigned*)(Ow + (size_t)orow * 2048 + d * 32 + r32) = cvtpk(v, vn); } }
;     }
.LBB0_635:
	s_waitcnt vmcnt(0)
	v_cmp_gt_u32_e32 vcc, 32, v213
	s_waitcnt vmcnt(0)
	s_barrier
	s_and_saveexec_b64 s[12:13], vcc
	s_mov_b32 s60, 0x2c000
	v_lshl_add_u32 v0, v231, 2, s26
	ds_write_b32 v0, v14
	s_or_b64 exec, exec, s[12:13]
	s_waitcnt lgkmcnt(0)
	v_add_u32_e32 v0, s26, v212
	ds_read_b128 v[112:115], v0
	ds_read_b128 v[116:119], v0 offset:32
	ds_read_b128 v[120:123], v0 offset:64
	ds_read_b128 v[124:127], v0 offset:96
	s_lshl_b32 s2, s11, 8
	s_add_u32 s2, s85, s2
	v_readlane_b32 s6, v255, 16
	s_nop 1
	s_addc_u32 s8, s6, 0
	s_ashr_i32 s77, s76, 31
	s_lshl_b64 s[6:7], s[76:77], 12
	s_add_u32 s6, s2, s6
	s_addc_u32 s7, s8, s7
	v_lshlrev_b32_e32 v14, 1, v231
	v_lshl_add_u32 v14, v232, 14, v14
	v_and_b32_e32 v0, 1, v230
	v_cmp_eq_u32_e64 s[12:13], 0, v0
	s_waitcnt lgkmcnt(0)
	v_rcp_f32_e32 v112, v112
	v_rcp_f32_e32 v113, v113
	v_rcp_f32_e32 v114, v114
	v_rcp_f32_e32 v115, v115
	v_rcp_f32_e32 v116, v116
	v_rcp_f32_e32 v117, v117
	v_rcp_f32_e32 v118, v118
	v_rcp_f32_e32 v119, v119
	v_rcp_f32_e32 v120, v120
	v_rcp_f32_e32 v121, v121
	v_rcp_f32_e32 v122, v122
	v_rcp_f32_e32 v123, v123
	v_rcp_f32_e32 v124, v124
	v_rcp_f32_e32 v125, v125
	v_rcp_f32_e32 v126, v126
	v_rcp_f32_e32 v127, v127
	s_nop 0
	v_pk_mul_f32 v[64:65], v[64:65], v[112:113]
	v_pk_mul_f32 v[66:67], v[66:67], v[114:115]
	v_pk_mul_f32 v[68:69], v[68:69], v[116:117]
	v_pk_mul_f32 v[70:71], v[70:71], v[118:119]
	v_pk_mul_f32 v[72:73], v[72:73], v[120:121]
	v_pk_mul_f32 v[74:75], v[74:75], v[122:123]
	v_pk_mul_f32 v[76:77], v[76:77], v[124:125]
	v_pk_mul_f32 v[78:79], v[78:79], v[126:127]
	v_pk_mul_f32 v[48:49], v[48:49], v[112:113]
	v_pk_mul_f32 v[50:51], v[50:51], v[114:115]
	v_pk_mul_f32 v[52:53], v[52:53], v[116:117]
	v_pk_mul_f32 v[54:55], v[54:55], v[118:119]
	v_pk_mul_f32 v[56:57], v[56:57], v[120:121]
	v_pk_mul_f32 v[58:59], v[58:59], v[122:123]
	v_pk_mul_f32 v[60:61], v[60:61], v[124:125]
	v_pk_mul_f32 v[62:63], v[62:63], v[126:127]
	v_pk_mul_f32 v[32:33], v[32:33], v[112:113]
	v_pk_mul_f32 v[34:35], v[34:35], v[114:115]
	v_pk_mul_f32 v[36:37], v[36:37], v[116:117]
	v_pk_mul_f32 v[38:39], v[38:39], v[118:119]
	v_pk_mul_f32 v[40:41], v[40:41], v[120:121]
	v_pk_mul_f32 v[42:43], v[42:43], v[122:123]
	v_pk_mul_f32 v[44:45], v[44:45], v[124:125]
	v_pk_mul_f32 v[46:47], v[46:47], v[126:127]
	v_pk_mul_f32 v[16:17], v[16:17], v[112:113]
	v_pk_mul_f32 v[18:19], v[18:19], v[114:115]
	v_pk_mul_f32 v[20:21], v[20:21], v[116:117]
	v_pk_mul_f32 v[22:23], v[22:23], v[118:119]
	v_pk_mul_f32 v[24:25], v[24:25], v[120:121]
	v_pk_mul_f32 v[26:27], v[26:27], v[122:123]
	v_pk_mul_f32 v[28:29], v[28:29], v[124:125]
	v_pk_mul_f32 v[30:31], v[30:31], v[126:127]
	v_mov_b32_dpp v128, v64 quad_perm:[1,0,3,2] row_mask:0xf bank_mask:0xf
	v_mov_b32_dpp v129, v65 quad_perm:[1,0,3,2] row_mask:0xf bank_mask:0xf
	v_mov_b32_dpp v130, v66 quad_perm:[1,0,3,2] row_mask:0xf bank_mask:0xf
	v_mov_b32_dpp v131, v67 quad_perm:[1,0,3,2] row_mask:0xf bank_mask:0xf
	v_mov_b32_dpp v132, v68 quad_perm:[1,0,3,2] row_mask:0xf bank_mask:0xf
	v_mov_b32_dpp v133, v69 quad_perm:[1,0,3,2] row_mask:0xf bank_mask:0xf
	v_mov_b32_dpp v134, v70 quad_perm:[1,0,3,2] row_mask:0xf bank_mask:0xf
	v_mov_b32_dpp v135, v71 quad_perm:[1,0,3,2] row_mask:0xf bank_mask:0xf
	v_mov_b32_dpp v136, v72 quad_perm:[1,0,3,2] row_mask:0xf bank_mask:0xf
	v_mov_b32_dpp v137, v73 quad_perm:[1,0,3,2] row_mask:0xf bank_mask:0xf
	v_mov_b32_dpp v138, v74 quad_perm:[1,0,3,2] row_mask:0xf bank_mask:0xf
	v_mov_b32_dpp v139, v75 quad_perm:[1,0,3,2] row_mask:0xf bank_mask:0xf
	v_mov_b32_dpp v140, v76 quad_perm:[1,0,3,2] row_mask:0xf bank_mask:0xf
	v_mov_b32_dpp v141, v77 quad_perm:[1,0,3,2] row_mask:0xf bank_mask:0xf
	v_mov_b32_dpp v142, v78 quad_perm:[1,0,3,2] row_mask:0xf bank_mask:0xf
	v_mov_b32_dpp v143, v79 quad_perm:[1,0,3,2] row_mask:0xf bank_mask:0xf
	v_cvt_pk_bf16_f32 v64, v64, v128
	v_cvt_pk_bf16_f32 v65, v65, v129
	v_cvt_pk_bf16_f32 v66, v66, v130
	v_cvt_pk_bf16_f32 v67, v67, v131
	v_cvt_pk_bf16_f32 v68, v68, v132
	v_cvt_pk_bf16_f32 v69, v69, v133
	v_cvt_pk_bf16_f32 v70, v70, v134
	v_cvt_pk_bf16_f32 v71, v71, v135
	v_cvt_pk_bf16_f32 v72, v72, v136
	v_cvt_pk_bf16_f32 v73, v73, v137
	v_cvt_pk_bf16_f32 v74, v74, v138
	v_cvt_pk_bf16_f32 v75, v75, v139
	v_cvt_pk_bf16_f32 v76, v76, v140
	v_cvt_pk_bf16_f32 v77, v77, v141
	v_cvt_pk_bf16_f32 v78, v78, v142
	v_cvt_pk_bf16_f32 v79, v79, v143
	v_mov_b32_dpp v128, v48 quad_perm:[1,0,3,2] row_mask:0xf bank_mask:0xf
	v_mov_b32_dpp v129, v49 quad_perm:[1,0,3,2] row_mask:0xf bank_mask:0xf
	v_mov_b32_dpp v130, v50 quad_perm:[1,0,3,2] row_mask:0xf bank_mask:0xf
	v_mov_b32_dpp v131, v51 quad_perm:[1,0,3,2] row_mask:0xf bank_mask:0xf
	v_mov_b32_dpp v132, v52 quad_perm:[1,0,3,2] row_mask:0xf bank_mask:0xf
	v_mov_b32_dpp v133, v53 quad_perm:[1,0,3,2] row_mask:0xf bank_mask:0xf
	v_mov_b32_dpp v134, v54 quad_perm:[1,0,3,2] row_mask:0xf bank_mask:0xf
	v_mov_b32_dpp v135, v55 quad_perm:[1,0,3,2] row_mask:0xf bank_mask:0xf
	v_mov_b32_dpp v136, v56 quad_perm:[1,0,3,2] row_mask:0xf bank_mask:0xf
	v_mov_b32_dpp v137, v57 quad_perm:[1,0,3,2] row_mask:0xf bank_mask:0xf
	v_mov_b32_dpp v138, v58 quad_perm:[1,0,3,2] row_mask:0xf bank_mask:0xf
	v_mov_b32_dpp v139, v59 quad_perm:[1,0,3,2] row_mask:0xf bank_mask:0xf
	v_mov_b32_dpp v140, v60 quad_perm:[1,0,3,2] row_mask:0xf bank_mask:0xf
	v_mov_b32_dpp v141, v61 quad_perm:[1,0,3,2] row_mask:0xf bank_mask:0xf
	v_mov_b32_dpp v142, v62 quad_perm:[1,0,3,2] row_mask:0xf bank_mask:0xf
	v_mov_b32_dpp v143, v63 quad_perm:[1,0,3,2] row_mask:0xf bank_mask:0xf
	v_cvt_pk_bf16_f32 v48, v48, v128
	v_cvt_pk_bf16_f32 v49, v49, v129
	v_cvt_pk_bf16_f32 v50, v50, v130
	v_cvt_pk_bf16_f32 v51, v51, v131
; __device__ __forceinline__ unsigned cvtpk(float lo, float hi) { const cvt_f32x2 v = {lo, hi}; const cvt_bf16x2 r = __builtin_convertvector(v, cvt_bf16x2); return __builtin_bit_cast(unsigned, r); }
; __device__ __forceinline__ int crow(int r, int hi) { return (r & 3) + 8 * (r >> 2) + 4 * hi; }
; template <int MODE, int VARI>
; __device__ __forceinline__ void attn_unit(LAS unsigned char* lds, const int tid, const AttnP& a, float c2, float lam, const float* subln, float outscale, float fox_u, const bool fast) {
;     ...
;     if (WIDE || wid < 4) {
;         bf16_t* Ow = a.O + (size_t)qpos0 * 2048;
; #pragma unroll
;         for (int r = 0; r < 16; ++r) { const int orow = crow(r, hi);
; #pragma unroll
;             for (int d = 0; d < 4; ++d) { const float v = o[d][r]; const float vn = __shfl_xor(v, 1);
;                 if ((r32 & 1) == 0) *(unsigned*)(Ow + (size_t)orow * 2048 + d * 32 + r32) = cvtpk(v, vn); } }
;     }
	v_cvt_pk_bf16_f32 v52, v52, v132
	v_cvt_pk_bf16_f32 v53, v53, v133
	v_cvt_pk_bf16_f32 v54, v54, v134
	v_cvt_pk_bf16_f32 v55, v55, v135
	v_cvt_pk_bf16_f32 v56, v56, v136
	v_cvt_pk_bf16_f32 v57, v57, v137
	v_cvt_pk_bf16_f32 v58, v58, v138
	v_cvt_pk_bf16_f32 v59, v59, v139
	v_cvt_pk_bf16_f32 v60, v60, v140
	v_cvt_pk_bf16_f32 v61, v61, v141
	v_cvt_pk_bf16_f32 v62, v62, v142
	v_cvt_pk_bf16_f32 v63, v63, v143
	v_mov_b32_dpp v128, v32 quad_perm:[1,0,3,2] row_mask:0xf bank_mask:0xf
	v_mov_b32_dpp v129, v33 quad_perm:[1,0,3,2] row_mask:0xf bank_mask:0xf
	v_mov_b32_dpp v130, v34 quad_perm:[1,0,3,2] row_mask:0xf bank_mask:0xf
	v_mov_b32_dpp v131, v35 quad_perm:[1,0,3,2] row_mask:0xf bank_mask:0xf
	v_mov_b32_dpp v132, v36 quad_perm:[1,0,3,2] row_mask:0xf bank_mask:0xf
	v_mov_b32_dpp v133, v37 quad_perm:[1,0,3,2] row_mask:0xf bank_mask:0xf
	v_mov_b32_dpp v134, v38 quad_perm:[1,0,3,2] row_mask:0xf bank_mask:0xf
	v_mov_b32_dpp v135, v39 quad_perm:[1,0,3,2] row_mask:0xf bank_mask:0xf
	v_mov_b32_dpp v136, v40 quad_perm:[1,0,3,2] row_mask:0xf bank_mask:0xf
	v_mov_b32_dpp v137, v41 quad_perm:[1,0,3,2] row_mask:0xf bank_mask:0xf
	v_mov_b32_dpp v138, v42 quad_perm:[1,0,3,2] row_mask:0xf bank_mask:0xf
	v_mov_b32_dpp v139, v43 quad_perm:[1,0,3,2] row_mask:0xf bank_mask:0xf
	v_mov_b32_dpp v140, v44 quad_perm:[1,0,3,2] row_mask:0xf bank_mask:0xf
	v_mov_b32_dpp v141, v45 quad_perm:[1,0,3,2] row_mask:0xf bank_mask:0xf
	v_mov_b32_dpp v142, v46 quad_perm:[1,0,3,2] row_mask:0xf bank_mask:0xf
	v_mov_b32_dpp v143, v47 quad_perm:[1,0,3,2] row_mask:0xf bank_mask:0xf
	v_cvt_pk_bf16_f32 v32, v32, v128
	v_cvt_pk_bf16_f32 v33, v33, v129
	v_cvt_pk_bf16_f32 v34, v34, v130
	v_cvt_pk_bf16_f32 v35, v35, v131
	v_cvt_pk_bf16_f32 v36, v36, v132
	v_cvt_pk_bf16_f32 v37, v37, v133
	v_cvt_pk_bf16_f32 v38, v38, v134
	v_cvt_pk_bf16_f32 v39, v39, v135
	v_cvt_pk_bf16_f32 v40, v40, v136
	v_cvt_pk_bf16_f32 v41, v41, v137
	v_cvt_pk_bf16_f32 v42, v42, v138
	v_cvt_pk_bf16_f32 v43, v43, v139
	v_cvt_pk_bf16_f32 v44, v44, v140
	v_cvt_pk_bf16_f32 v45, v45, v141
	v_cvt_pk_bf16_f32 v46, v46, v142
	v_cvt_pk_bf16_f32 v47, v47, v143
	v_mov_b32_dpp v128, v16 quad_perm:[1,0,3,2] row_mask:0xf bank_mask:0xf
	v_mov_b32_dpp v129, v17 quad_perm:[1,0,3,2] row_mask:0xf bank_mask:0xf
	v_mov_b32_dpp v130, v18 quad_perm:[1,0,3,2] row_mask:0xf bank_mask:0xf
	v_mov_b32_dpp v131, v19 quad_perm:[1,0,3,2] row_mask:0xf bank_mask:0xf
	v_mov_b32_dpp v132, v20 quad_perm:[1,0,3,2] row_mask:0xf bank_mask:0xf
	v_mov_b32_dpp v133, v21 quad_perm:[1,0,3,2] row_mask:0xf bank_mask:0xf
	v_mov_b32_dpp v134, v22 quad_perm:[1,0,3,2] row_mask:0xf bank_mask:0xf
	v_mov_b32_dpp v135, v23 quad_perm:[1,0,3,2] row_mask:0xf bank_mask:0xf
	v_mov_b32_dpp v136, v24 quad_perm:[1,0,3,2] row_mask:0xf bank_mask:0xf
	v_mov_b32_dpp v137, v25 quad_perm:[1,0,3,2] row_mask:0xf bank_mask:0xf
	v_mov_b32_dpp v138, v26 quad_perm:[1,0,3,2] row_mask:0xf bank_mask:0xf
	v_mov_b32_dpp v139, v27 quad_perm:[1,0,3,2] row_mask:0xf bank_mask:0xf
	v_mov_b32_dpp v140, v28 quad_perm:[1,0,3,2] row_mask:0xf bank_mask:0xf
	v_mov_b32_dpp v141, v29 quad_perm:[1,0,3,2] row_mask:0xf bank_mask:0xf
	v_mov_b32_dpp v142, v30 quad_perm:[1,0,3,2] row_mask:0xf bank_mask:0xf
	v_mov_b32_dpp v143, v31 quad_perm:[1,0,3,2] row_mask:0xf bank_mask:0xf
	v_cvt_pk_bf16_f32 v16, v16, v128
	v_cvt_pk_bf16_f32 v17, v17, v129
	v_cvt_pk_bf16_f32 v18, v18, v130
	v_cvt_pk_bf16_f32 v19, v19, v131
	v_cvt_pk_bf16_f32 v20, v20, v132
	v_cvt_pk_bf16_f32 v21, v21, v133
	v_cvt_pk_bf16_f32 v22, v22, v134
	v_cvt_pk_bf16_f32 v23, v23, v135
	v_cvt_pk_bf16_f32 v24, v24, v136
	v_cvt_pk_bf16_f32 v25, v25, v137
	v_cvt_pk_bf16_f32 v26, v26, v138
	v_cvt_pk_bf16_f32 v27, v27, v139
; __device__ __forceinline__ unsigned cvtpk(float lo, float hi) { const cvt_f32x2 v = {lo, hi}; const cvt_bf16x2 r = __builtin_convertvector(v, cvt_bf16x2); return __builtin_bit_cast(unsigned, r); }
; __device__ __forceinline__ int crow(int r, int hi) { return (r & 3) + 8 * (r >> 2) + 4 * hi; }
; template <int MODE, int VARI>
; __device__ __forceinline__ void attn_unit(LAS unsigned char* lds, const int tid, const AttnP& a, float c2, float lam, const float* subln, float outscale, float fox_u, const bool fast) {
;     ...
;     if (WIDE || wid < 4) {
;         bf16_t* Ow = a.O + (size_t)qpos0 * 2048;
; #pragma unroll
;         for (int r = 0; r < 16; ++r) { const int orow = crow(r, hi);
; #pragma unroll
;             for (int d = 0; d < 4; ++d) { const float v = o[d][r]; const float vn = __shfl_xor(v, 1);
;                 if ((r32 & 1) == 0) *(unsigned*)(Ow + (size_t)orow * 2048 + d * 32 + r32) = cvtpk(v, vn); } }
;     }
	v_cvt_pk_bf16_f32 v28, v28, v140
	v_cvt_pk_bf16_f32 v29, v29, v141
	v_cvt_pk_bf16_f32 v30, v30, v142
	v_cvt_pk_bf16_f32 v31, v31, v143
	v_mov_b32_e32 v112, v14
	v_add_u32_e32 v113, 0x1000, v14
	v_add_u32_e32 v114, 0x2000, v14
	v_add_u32_e32 v115, 0x3000, v14
	v_add_u32_e32 v116, 0x8000, v14
	v_add_u32_e32 v117, 0x9000, v14
	v_add_u32_e32 v118, 0xa000, v14
	v_add_u32_e32 v119, 0xb000, v14
	v_add_u32_e32 v120, 0x10000, v14
	v_add_u32_e32 v121, 0x11000, v14
	v_add_u32_e32 v122, 0x12000, v14
	v_add_u32_e32 v123, 0x13000, v14
	v_add_u32_e32 v124, 0x18000, v14
	v_add_u32_e32 v125, 0x19000, v14
	v_add_u32_e32 v126, 0x1a000, v14
	v_add_u32_e32 v127, 0x1b000, v14
	s_and_saveexec_b64 s[14:15], s[12:13]
	global_store_dword v112, v64, s[6:7]
	global_store_dword v112, v48, s[6:7] offset:64
	global_store_dword v112, v32, s[6:7] offset:128
	global_store_dword v112, v16, s[6:7] offset:192
	global_store_dword v113, v65, s[6:7]
	global_store_dword v113, v49, s[6:7] offset:64
	global_store_dword v113, v33, s[6:7] offset:128
	global_store_dword v113, v17, s[6:7] offset:192
	global_store_dword v114, v66, s[6:7]
	global_store_dword v114, v50, s[6:7] offset:64
	global_store_dword v114, v34, s[6:7] offset:128
	global_store_dword v114, v18, s[6:7] offset:192
	global_store_dword v115, v67, s[6:7]
	global_store_dword v115, v51, s[6:7] offset:64
	global_store_dword v115, v35, s[6:7] offset:128
	global_store_dword v115, v19, s[6:7] offset:192
	global_store_dword v116, v68, s[6:7]
	global_store_dword v116, v52, s[6:7] offset:64
	global_store_dword v116, v36, s[6:7] offset:128
	global_store_dword v116, v20, s[6:7] offset:192
	global_store_dword v117, v69, s[6:7]
	global_store_dword v117, v53, s[6:7] offset:64
	global_store_dword v117, v37, s[6:7] offset:128
	global_store_dword v117, v21, s[6:7] offset:192
	global_store_dword v118, v70, s[6:7]
	global_store_dword v118, v54, s[6:7] offset:64
	global_store_dword v118, v38, s[6:7] offset:128
	global_store_dword v118, v22, s[6:7] offset:192
	global_store_dword v119, v71, s[6:7]
	global_store_dword v119, v55, s[6:7] offset:64
	global_store_dword v119, v39, s[6:7] offset:128
	global_store_dword v119, v23, s[6:7] offset:192
	global_store_dword v120, v72, s[6:7]
	global_store_dword v120, v56, s[6:7] offset:64
	global_store_dword v120, v40, s[6:7] offset:128
	global_store_dword v120, v24, s[6:7] offset:192
	global_store_dword v121, v73, s[6:7]
	global_store_dword v121, v57, s[6:7] offset:64
	global_store_dword v121, v41, s[6:7] offset:128
	global_store_dword v121, v25, s[6:7] offset:192
	global_store_dword v122, v74, s[6:7]
	global_store_dword v122, v58, s[6:7] offset:64
	global_store_dword v122, v42, s[6:7] offset:128
	global_store_dword v122, v26, s[6:7] offset:192
	global_store_dword v123, v75, s[6:7]
	global_store_dword v123, v59, s[6:7] offset:64
	global_store_dword v123, v43, s[6:7] offset:128
	global_store_dword v123, v27, s[6:7] offset:192
	global_store_dword v124, v76, s[6:7]
	global_store_dword v124, v60, s[6:7] offset:64
	global_store_dword v124, v44, s[6:7] offset:128
	global_store_dword v124, v28, s[6:7] offset:192
	global_store_dword v125, v77, s[6:7]
	global_store_dword v125, v61, s[6:7] offset:64
	global_store_dword v125, v45, s[6:7] offset:128
	global_store_dword v125, v29, s[6:7] offset:192
	global_store_dword v126, v78, s[6:7]
	global_store_dword v126, v62, s[6:7] offset:64
	global_store_dword v126, v46, s[6:7] offset:128
	global_store_dword v126, v30, s[6:7] offset:192
	global_store_dword v127, v79, s[6:7]
	global_store_dword v127, v63, s[6:7] offset:64
	global_store_dword v127, v47, s[6:7] offset:128
	global_store_dword v127, v31, s[6:7] offset:192

; __device__ __forceinline__ unsigned cvtpk(float lo, float hi) { const cvt_f32x2 v = {lo, hi}; const cvt_bf16x2 r = __builtin_convertvector(v, cvt_bf16x2); return __builtin_bit_cast(unsigned, r); }
; __device__ __forceinline__ int crow(int r, int hi) { return (r & 3) + 8 * (r >> 2) + 4 * hi; }
; template <int MODE, int VARI>
; __device__ __forceinline__ void attn_unit(LAS unsigned char* lds, const int tid, const AttnP& a, float c2, float lam, const float* subln, float outscale, float fox_u, const bool fast) {
;     ...
;         if (wid < 4) {
;             const float g0 = subln[r32], g1 = subln[32 + r32], g2 = subln[64 + r32], g3 = subln[96 + r32];
; #pragma unroll
;             for (int r = 0; r < 16; ++r) {
;                 float v[4]; float ss = 0.f;
; #pragma unroll
;                 for (int d = 0; d < 4; ++d) { v[d] = o[d][r] - lam * X[(d * 16 + r) * 64]; ss += v[d] * v[d]; }
;                 ss += __shfl_xor(ss, 1); ss += __shfl_xor(ss, 2); ss += __shfl_xor(ss, 4); ss += __shfl_xor(ss, 8); ss += __shfl_xor(ss, 16);
;                 const float rs = rsqrtf(ss * (1.0f / 128.0f) + RMS_EPS) * outscale;
;                 o[0][r] = v[0] * rs * g0; o[1][r] = v[1] * rs * g1; o[2][r] = v[2] * rs * g2; o[3][r] = v[3] * rs * g3;
;             }
;     ...
;     if (WIDE || wid < 4) {
;         bf16_t* Ow = a.O + (size_t)qpos0 * 2048;
; #pragma unroll
;         for (int r = 0; r < 16; ++r) { const int orow = crow(r, hi);
; #pragma unroll
;             for (int d = 0; d < 4; ++d) { const float v = o[d][r]; const float vn = __shfl_xor(v, 1);
;                 if ((r32 & 1) == 0) *(unsigned*)(Ow + (size_t)orow * 2048 + d * 32 + r32) = cvtpk(v, vn); } }
;     }
.LBB0_833:
	s_or_b64 exec, exec, s[14:15]
	v_mul_f32_e32 v0, v19, v109
	s_waitcnt vmcnt(2)
	v_mul_f32_e32 v0, v103, v0
	s_nop 1
	v_mov_b32_dpp v18, v0 quad_perm:[1,0,3,2] row_mask:0xf bank_mask:0xf
	s_and_saveexec_b64 s[14:15], s[12:13]
	s_cbranch_execz .LBB0_835
	s_waitcnt lgkmcnt(0)
	v_cvt_pk_bf16_f32 v0, v0, v18
	global_store_dword v[16:17], v0, off offset:64
.LBB0_835:
	s_or_b64 exec, exec, s[14:15]
	v_mul_f32_e32 v0, v6, v109
	s_waitcnt vmcnt(1)
	v_mul_f32_e32 v0, v105, v0
	s_nop 1
	v_mov_b32_dpp v6, v0 quad_perm:[1,0,3,2] row_mask:0xf bank_mask:0xf
	s_and_saveexec_b64 s[14:15], s[12:13]
	s_cbranch_execz .LBB0_837
	s_waitcnt lgkmcnt(0)
	v_cvt_pk_bf16_f32 v0, v0, v6
	global_store_dword v[16:17], v0, off offset:128
.LBB0_837:
	s_or_b64 exec, exec, s[14:15]
	v_mul_f32_e32 v0, v7, v109
	s_waitcnt vmcnt(0)
	v_mul_f32_e32 v0, v21, v0
	s_waitcnt lgkmcnt(0)
	s_nop 1
	v_mov_b32_dpp v6, v0 quad_perm:[1,0,3,2] row_mask:0xf bank_mask:0xf
	s_and_saveexec_b64 s[14:15], s[12:13]
	s_cbranch_execz .LBB0_839
	s_waitcnt lgkmcnt(0)
	v_cvt_pk_bf16_f32 v0, v0, v6
	global_store_dword v[16:17], v0, off offset:192
.LBB0_839:
	s_or_b64 exec, exec, s[14:15]
	v_mul_f32_e32 v0, 0x4b800000, v20
	v_cndmask_b32_e32 v0, v20, v0, vcc
	v_rsq_f32_e32 v0, v0
	s_waitcnt lgkmcnt(0)
	v_mul_f32_e32 v6, 0x45800000, v0
	v_cndmask_b32_e32 v0, v0, v6, vcc
	v_mul_f32_e32 v0, v229, v0
	v_mul_f32_e32 v4, v4, v0
	v_mul_f32_e32 v4, v104, v4
	s_nop 1
	v_mov_b32_dpp v6, v4 quad_perm:[1,0,3,2] row_mask:0xf bank_mask:0xf
	s_and_saveexec_b64 s[14:15], s[12:13]
	s_cbranch_execz .LBB0_841
	s_waitcnt lgkmcnt(0)
	v_cvt_pk_bf16_f32 v4, v4, v6
	v_add_co_u32_e32 v6, vcc, 0x1000, v16
	s_nop 1
	v_addc_co_u32_e32 v7, vcc, 0, v17, vcc
	global_store_dword v[6:7], v4, off
.LBB0_841:
	s_or_b64 exec, exec, s[14:15]
	v_mul_f32_e32 v4, v5, v0
	v_mul_f32_e32 v4, v103, v4
	s_nop 1
	v_mov_b32_dpp v5, v4 quad_perm:[1,0,3,2] row_mask:0xf bank_mask:0xf
	s_and_saveexec_b64 s[14:15], s[12:13]
	s_cbranch_execz .LBB0_843
	s_waitcnt lgkmcnt(0)
	v_cvt_pk_bf16_f32 v6, v4, v5
	v_add_co_u32_e32 v4, vcc, 0x1000, v16
	s_nop 1
	v_addc_co_u32_e32 v5, vcc, 0, v17, vcc
	global_store_dword v[4:5], v6, off offset:64
.LBB0_843:
	s_or_b64 exec, exec, s[14:15]
	v_mul_f32_e32 v2, v2, v0
	v_mul_f32_e32 v2, v105, v2
	s_nop 1
	v_mov_b32_dpp v4, v2 quad_perm:[1,0,3,2] row_mask:0xf bank_mask:0xf
	s_and_saveexec_b64 s[14:15], s[12:13]
	s_cbranch_execz .LBB0_845
	s_waitcnt lgkmcnt(0)
	v_cvt_pk_bf16_f32 v2, v2, v4
	v_add_co_u32_e32 v4, vcc, 0x1000, v16
	s_nop 1
	v_addc_co_u32_e32 v5, vcc, 0, v17, vcc
	global_store_dword v[4:5], v2, off offset:128
.LBB0_845:
	s_or_b64 exec, exec, s[14:15]
	v_mul_f32_e32 v0, v3, v0
	v_mul_f32_e32 v0, v21, v0
	s_nop 1
	v_mov_b32_dpp v2, v0 quad_perm:[1,0,3,2] row_mask:0xf bank_mask:0xf
	s_and_saveexec_b64 s[14:15], s[12:13]
	s_cbranch_execz .LBB0_847
	s_waitcnt lgkmcnt(0)
	v_cvt_pk_bf16_f32 v0, v0, v2
	v_add_co_u32_e32 v2, vcc, 0x1000, v16
	s_nop 1
	v_addc_co_u32_e32 v3, vcc, 0, v17, vcc
	global_store_dword v[2:3], v0, off offset:192
.LBB0_847:
	s_or_b64 exec, exec, s[14:15]
	s_waitcnt lgkmcnt(0)
	v_pk_add_f32 v[2:3], v[86:87], v[88:89]
	s_brev_b32 s2, 60
	v_pk_fma_f32 v[2:3], v[2:3], s[2:3], v[198:199] op_sel_hi:[1,0,0]
	s_nop 0
	v_mul_f32_e32 v0, 0x4b800000, v3
	v_cmp_gt_f32_e32 vcc, s16, v3
	v_cmp_gt_f32_e64 s[14:15], s16, v2
	s_nop 0
	v_cndmask_b32_e32 v0, v3, v0, vcc
	v_rsq_f32_e32 v0, v0
	s_nop 0
	v_mul_f32_e32 v3, 0x45800000, v0
	v_cndmask_b32_e32 v0, v0, v3, vcc
	v_mul_f32_e32 v0, v229, v0
	v_mul_f32_e32 v3, v32, v0
	v_mul_f32_e32 v3, v104, v3
	s_nop 1
	v_mov_b32_dpp v4, v3 quad_perm:[1,0,3,2] row_mask:0xf bank_mask:0xf
	s_and_saveexec_b64 s[18:19], s[12:13]
	s_cbranch_execz .LBB0_849
	s_waitcnt lgkmcnt(0)
	v_cvt_pk_bf16_f32 v3, v3, v4
	v_add_co_u32_e32 v4, vcc, 0x2000, v16
	s_nop 1
	v_addc_co_u32_e32 v5, vcc, 0, v17, vcc
	global_store_dword v[4:5], v3, off
.LBB0_849:
	s_or_b64 exec, exec, s[18:19]
	v_mul_f32_e32 v3, v33, v0
	v_mul_f32_e32 v3, v103, v3
	s_waitcnt lgkmcnt(0)
	s_nop 1
	v_mov_b32_dpp v4, v3 quad_perm:[1,0,3,2] row_mask:0xf bank_mask:0xf
	s_and_saveexec_b64 s[18:19], s[12:13]
	s_cbranch_execz .LBB0_851
	s_waitcnt lgkmcnt(0)
	v_cvt_pk_bf16_f32 v3, v3, v4
	v_add_co_u32_e32 v4, vcc, 0x2000, v16
	s_nop 1
	v_addc_co_u32_e32 v5, vcc, 0, v17, vcc
	global_store_dword v[4:5], v3, off offset:64
.LBB0_851:
	s_or_b64 exec, exec, s[18:19]
	v_mul_f32_e32 v3, v26, v0
	v_mul_f32_e32 v3, v105, v3
	s_waitcnt lgkmcnt(0)
	s_nop 1
	v_mov_b32_dpp v4, v3 quad_perm:[1,0,3,2] row_mask:0xf bank_mask:0xf
	s_and_saveexec_b64 s[18:19], s[12:13]
	s_cbranch_execz .LBB0_853
	s_waitcnt lgkmcnt(0)
	v_cvt_pk_bf16_f32 v3, v3, v4
	v_add_co_u32_e32 v4, vcc, 0x2000, v16
	s_nop 1
	v_addc_co_u32_e32 v5, vcc, 0, v17, vcc
	global_store_dword v[4:5], v3, off offset:128
.LBB0_853:
	s_or_b64 exec, exec, s[18:19]
	v_mul_f32_e32 v0, v27, v0
	v_mul_f32_e32 v0, v21, v0
	s_nop 1
	v_mov_b32_dpp v3, v0 quad_perm:[1,0,3,2] row_mask:0xf bank_mask:0xf
	s_and_saveexec_b64 s[18:19], s[12:13]
	s_cbranch_execz .LBB0_855
	s_waitcnt lgkmcnt(1)
	v_add_co_u32_e32 v4, vcc, 0x2000, v16
	s_waitcnt lgkmcnt(0)
	v_cvt_pk_bf16_f32 v0, v0, v3
	v_addc_co_u32_e32 v5, vcc, 0, v17, vcc
	global_store_dword v[4:5], v0, off offset:192
.LBB0_855:
	s_or_b64 exec, exec, s[18:19]
	v_mul_f32_e32 v0, 0x4b800000, v2
	v_cndmask_b32_e64 v0, v2, v0, s[14:15]
	v_rsq_f32_e32 v0, v0
	s_nop 0
	v_mul_f32_e32 v2, 0x45800000, v0
	v_cndmask_b32_e64 v0, v0, v2, s[14:15]
	v_mul_f32_e32 v0, v229, v0
	v_mul_f32_e32 v2, v22, v0
	v_mul_f32_e32 v2, v104, v2
	s_waitcnt lgkmcnt(0)
	s_nop 1
	v_mov_b32_dpp v3, v2 quad_perm:[1,0,3,2] row_mask:0xf bank_mask:0xf
	s_and_saveexec_b64 s[14:15], s[12:13]
	s_cbranch_execz .LBB0_857
	s_waitcnt lgkmcnt(0)
	v_cvt_pk_bf16_f32 v4, v2, v3
	v_add_co_u32_e32 v2, vcc, 0x3000, v16
	s_nop 1
	v_addc_co_u32_e32 v3, vcc, 0, v17, vcc
	global_store_dword v[2:3], v4, off
; __device__ __forceinline__ unsigned cvtpk(float lo, float hi) { const cvt_f32x2 v = {lo, hi}; const cvt_bf16x2 r = __builtin_convertvector(v, cvt_bf16x2); return __builtin_bit_cast(unsigned, r); }
; __device__ __forceinline__ int crow(int r, int hi) { return (r & 3) + 8 * (r >> 2) + 4 * hi; }
; template <int MODE, int VARI>
; __device__ __forceinline__ void attn_unit(LAS unsigned char* lds, const int tid, const AttnP& a, float c2, float lam, const float* subln, float outscale, float fox_u, const bool fast) {
;     ...
;         if (wid < 4) {
;             const float g0 = subln[r32], g1 = subln[32 + r32], g2 = subln[64 + r32], g3 = subln[96 + r32];
; #pragma unroll
;             for (int r = 0; r < 16; ++r) {
;                 float v[4]; float ss = 0.f;
; #pragma unroll
;                 for (int d = 0; d < 4; ++d) { v[d] = o[d][r] - lam * X[(d * 16 + r) * 64]; ss += v[d] * v[d]; }
;                 ss += __shfl_xor(ss, 1); ss += __shfl_xor(ss, 2); ss += __shfl_xor(ss, 4); ss += __shfl_xor(ss, 8); ss += __shfl_xor(ss, 16);
;                 const float rs = rsqrtf(ss * (1.0f / 128.0f) + RMS_EPS) * outscale;
;                 o[0][r] = v[0] * rs * g0; o[1][r] = v[1] * rs * g1; o[2][r] = v[2] * rs * g2; o[3][r] = v[3] * rs * g3;
;             }
;     ...
;     if (WIDE || wid < 4) {
;         bf16_t* Ow = a.O + (size_t)qpos0 * 2048;
; #pragma unroll
;         for (int r = 0; r < 16; ++r) { const int orow = crow(r, hi);
; #pragma unroll
;             for (int d = 0; d < 4; ++d) { const float v = o[d][r]; const float vn = __shfl_xor(v, 1);
;                 if ((r32 & 1) == 0) *(unsigned*)(Ow + (size_t)orow * 2048 + d * 32 + r32) = cvtpk(v, vn); } }
;     }
.LBB0_857:
	s_or_b64 exec, exec, s[14:15]
	v_mul_f32_e32 v2, v23, v0
	v_mul_f32_e32 v2, v103, v2
	s_waitcnt lgkmcnt(0)
	s_nop 1
	v_mov_b32_dpp v3, v2 quad_perm:[1,0,3,2] row_mask:0xf bank_mask:0xf
	s_and_saveexec_b64 s[14:15], s[12:13]
	s_cbranch_execz .LBB0_859
	s_waitcnt lgkmcnt(0)
	v_cvt_pk_bf16_f32 v4, v2, v3
	v_add_co_u32_e32 v2, vcc, 0x3000, v16
	s_nop 1
	v_addc_co_u32_e32 v3, vcc, 0, v17, vcc
	global_store_dword v[2:3], v4, off offset:64
.LBB0_859:
	s_or_b64 exec, exec, s[14:15]
	v_mul_f32_e32 v2, v8, v0
	v_mul_f32_e32 v2, v105, v2
	s_waitcnt lgkmcnt(0)
	s_nop 1
	v_mov_b32_dpp v3, v2 quad_perm:[1,0,3,2] row_mask:0xf bank_mask:0xf
	s_and_saveexec_b64 s[14:15], s[12:13]
	s_cbranch_execz .LBB0_861
	s_waitcnt lgkmcnt(0)
	v_cvt_pk_bf16_f32 v4, v2, v3
	v_add_co_u32_e32 v2, vcc, 0x3000, v16
	s_nop 1
	v_addc_co_u32_e32 v3, vcc, 0, v17, vcc
	global_store_dword v[2:3], v4, off offset:128
.LBB0_861:
	s_or_b64 exec, exec, s[14:15]
	v_mul_f32_e32 v0, v9, v0
	v_mul_f32_e32 v0, v21, v0
	s_nop 1
	v_mov_b32_dpp v2, v0 quad_perm:[1,0,3,2] row_mask:0xf bank_mask:0xf
	s_and_saveexec_b64 s[14:15], s[12:13]
	s_cbranch_execz .LBB0_863
	s_waitcnt lgkmcnt(0)
	v_cvt_pk_bf16_f32 v0, v0, v2
	v_add_co_u32_e32 v2, vcc, 0x3000, v16
	s_nop 1
	v_addc_co_u32_e32 v3, vcc, 0, v17, vcc
	global_store_dword v[2:3], v0, off offset:192
.LBB0_863:
	s_or_b64 exec, exec, s[14:15]
	s_waitcnt lgkmcnt(0)
	v_pk_add_f32 v[2:3], v[78:79], v[84:85]
	s_nop 0
	v_pk_fma_f32 v[2:3], v[2:3], s[2:3], v[198:199] op_sel_hi:[1,0,0]
	s_nop 0
	v_mul_f32_e32 v0, 0x4b800000, v3
	v_cmp_gt_f32_e32 vcc, s16, v3
	v_cmp_gt_f32_e64 s[14:15], s16, v2
	s_nop 0
	v_cndmask_b32_e32 v0, v3, v0, vcc
	v_rsq_f32_e32 v0, v0
	s_nop 0
	v_mul_f32_e32 v3, 0x45800000, v0
	v_cndmask_b32_e32 v0, v0, v3, vcc
	v_mul_f32_e32 v0, v229, v0
	v_mul_f32_e32 v3, v34, v0
	v_mul_f32_e32 v3, v104, v3
	s_nop 1
	v_mov_b32_dpp v4, v3 quad_perm:[1,0,3,2] row_mask:0xf bank_mask:0xf
	s_and_saveexec_b64 s[18:19], s[12:13]
	s_cbranch_execz .LBB0_865
	s_waitcnt lgkmcnt(0)
	v_cvt_pk_bf16_f32 v3, v3, v4
	v_add_co_u32_e32 v4, vcc, 0x8000, v16
	s_nop 1
	v_addc_co_u32_e32 v5, vcc, 0, v17, vcc
	global_store_dword v[4:5], v3, off
.LBB0_865:
	s_or_b64 exec, exec, s[18:19]
	v_mul_f32_e32 v3, v35, v0
	v_mul_f32_e32 v3, v103, v3
	s_waitcnt lgkmcnt(0)
	s_nop 1
	v_mov_b32_dpp v4, v3 quad_perm:[1,0,3,2] row_mask:0xf bank_mask:0xf
	s_and_saveexec_b64 s[18:19], s[12:13]
	s_cbranch_execz .LBB0_867
	s_waitcnt lgkmcnt(0)
	v_cvt_pk_bf16_f32 v3, v3, v4
	v_add_co_u32_e32 v4, vcc, 0x8000, v16
	s_nop 1
	v_addc_co_u32_e32 v5, vcc, 0, v17, vcc
	global_store_dword v[4:5], v3, off offset:64
.LBB0_867:
	s_or_b64 exec, exec, s[18:19]
	v_mul_f32_e32 v3, v28, v0
	v_mul_f32_e32 v3, v105, v3
	s_waitcnt lgkmcnt(0)
	s_nop 1
	v_mov_b32_dpp v4, v3 quad_perm:[1,0,3,2] row_mask:0xf bank_mask:0xf
	s_and_saveexec_b64 s[18:19], s[12:13]
	s_cbranch_execz .LBB0_869
	s_waitcnt lgkmcnt(0)
	v_cvt_pk_bf16_f32 v3, v3, v4
	v_add_co_u32_e32 v4, vcc, 0x8000, v16
	s_nop 1
	v_addc_co_u32_e32 v5, vcc, 0, v17, vcc
	global_store_dword v[4:5], v3, off offset:128
.LBB0_869:
	s_or_b64 exec, exec, s[18:19]
	v_mul_f32_e32 v0, v29, v0
	v_mul_f32_e32 v0, v21, v0
	s_nop 1
	v_mov_b32_dpp v3, v0 quad_perm:[1,0,3,2] row_mask:0xf bank_mask:0xf
	s_and_saveexec_b64 s[18:19], s[12:13]
	s_cbranch_execz .LBB0_871
	s_waitcnt lgkmcnt(1)
	v_add_co_u32_e32 v4, vcc, 0x8000, v16
	s_waitcnt lgkmcnt(0)
	v_cvt_pk_bf16_f32 v0, v0, v3
	v_addc_co_u32_e32 v5, vcc, 0, v17, vcc
	global_store_dword v[4:5], v0, off offset:192
.LBB0_871:
	s_or_b64 exec, exec, s[18:19]
	v_mul_f32_e32 v0, 0x4b800000, v2
	v_cndmask_b32_e64 v0, v2, v0, s[14:15]
	v_rsq_f32_e32 v0, v0
	s_nop 0
	v_mul_f32_e32 v2, 0x45800000, v0
	v_cndmask_b32_e64 v0, v0, v2, s[14:15]
	v_mul_f32_e32 v0, v229, v0
	v_mul_f32_e32 v2, v24, v0
	v_mul_f32_e32 v2, v104, v2
	s_waitcnt lgkmcnt(0)
	s_nop 1
	v_mov_b32_dpp v3, v2 quad_perm:[1,0,3,2] row_mask:0xf bank_mask:0xf
	s_and_saveexec_b64 s[14:15], s[12:13]
	s_cbranch_execz .LBB0_873
	s_waitcnt lgkmcnt(0)
	v_cvt_pk_bf16_f32 v4, v2, v3
	v_add_co_u32_e32 v2, vcc, 0x9000, v16
	s_nop 1
	v_addc_co_u32_e32 v3, vcc, 0, v17, vcc
	global_store_dword v[2:3], v4, off
.LBB0_873:
	s_or_b64 exec, exec, s[14:15]
	v_mul_f32_e32 v2, v25, v0
	v_mul_f32_e32 v2, v103, v2
	s_waitcnt lgkmcnt(0)
	s_nop 1
	v_mov_b32_dpp v3, v2 quad_perm:[1,0,3,2] row_mask:0xf bank_mask:0xf
	s_and_saveexec_b64 s[14:15], s[12:13]
	s_cbranch_execz .LBB0_875
	s_waitcnt lgkmcnt(0)
	v_cvt_pk_bf16_f32 v4, v2, v3
	v_add_co_u32_e32 v2, vcc, 0x9000, v16
	s_nop 1
	v_addc_co_u32_e32 v3, vcc, 0, v17, vcc
	global_store_dword v[2:3], v4, off offset:64
.LBB0_875:
	s_or_b64 exec, exec, s[14:15]
	v_mul_f32_e32 v2, v10, v0
	v_mul_f32_e32 v2, v105, v2
	s_waitcnt lgkmcnt(0)
	s_nop 1
	v_mov_b32_dpp v3, v2 quad_perm:[1,0,3,2] row_mask:0xf bank_mask:0xf
	s_and_saveexec_b64 s[14:15], s[12:13]
	s_cbranch_execz .LBB0_877
	s_waitcnt lgkmcnt(0)
	v_cvt_pk_bf16_f32 v4, v2, v3
	v_add_co_u32_e32 v2, vcc, 0x9000, v16
	s_nop 1
	v_addc_co_u32_e32 v3, vcc, 0, v17, vcc
	global_store_dword v[2:3], v4, off offset:128
.LBB0_877:
	s_or_b64 exec, exec, s[14:15]
	v_mul_f32_e32 v0, v11, v0
	v_mul_f32_e32 v0, v21, v0
	s_nop 1
	v_mov_b32_dpp v2, v0 quad_perm:[1,0,3,2] row_mask:0xf bank_mask:0xf
	s_and_saveexec_b64 s[14:15], s[12:13]
	s_cbranch_execz .LBB0_879
	s_waitcnt lgkmcnt(0)
	v_cvt_pk_bf16_f32 v0, v0, v2
	v_add_co_u32_e32 v2, vcc, 0x9000, v16
	s_nop 1
	v_addc_co_u32_e32 v3, vcc, 0, v17, vcc
	global_store_dword v[2:3], v0, off offset:192
; __device__ __forceinline__ unsigned cvtpk(float lo, float hi) { const cvt_f32x2 v = {lo, hi}; const cvt_bf16x2 r = __builtin_convertvector(v, cvt_bf16x2); return __builtin_bit_cast(unsigned, r); }
; __device__ __forceinline__ int crow(int r, int hi) { return (r & 3) + 8 * (r >> 2) + 4 * hi; }
; template <int MODE, int VARI>
; __device__ __forceinline__ void attn_unit(LAS unsigned char* lds, const int tid, const AttnP& a, float c2, float lam, const float* subln, float outscale, float fox_u, const bool fast) {
;     ...
;         if (wid < 4) {
;             const float g0 = subln[r32], g1 = subln[32 + r32], g2 = subln[64 + r32], g3 = subln[96 + r32];
; #pragma unroll
;             for (int r = 0; r < 16; ++r) {
;                 float v[4]; float ss = 0.f;
; #pragma unroll
;                 for (int d = 0; d < 4; ++d) { v[d] = o[d][r] - lam * X[(d * 16 + r) * 64]; ss += v[d] * v[d]; }
;                 ss += __shfl_xor(ss, 1); ss += __shfl_xor(ss, 2); ss += __shfl_xor(ss, 4); ss += __shfl_xor(ss, 8); ss += __shfl_xor(ss, 16);
;                 const float rs = rsqrtf(ss * (1.0f / 128.0f) + RMS_EPS) * outscale;
;                 o[0][r] = v[0] * rs * g0; o[1][r] = v[1] * rs * g1; o[2][r] = v[2] * rs * g2; o[3][r] = v[3] * rs * g3;
;             }
;     ...
;     if (WIDE || wid < 4) {
;         bf16_t* Ow = a.O + (size_t)qpos0 * 2048;
; #pragma unroll
;         for (int r = 0; r < 16; ++r) { const int orow = crow(r, hi);
; #pragma unroll
;             for (int d = 0; d < 4; ++d) { const float v = o[d][r]; const float vn = __shfl_xor(v, 1);
;                 if ((r32 & 1) == 0) *(unsigned*)(Ow + (size_t)orow * 2048 + d * 32 + r32) = cvtpk(v, vn); } }
;     }
.LBB0_879:
	s_or_b64 exec, exec, s[14:15]
	s_waitcnt lgkmcnt(0)
	v_pk_add_f32 v[2:3], v[76:77], v[80:81]
	s_nop 0
	v_pk_fma_f32 v[2:3], v[2:3], s[2:3], v[198:199] op_sel_hi:[1,0,0]
	s_nop 0
	v_mul_f32_e32 v0, 0x4b800000, v3
	v_cmp_gt_f32_e32 vcc, s16, v3
	v_cmp_gt_f32_e64 s[14:15], s16, v2
	s_nop 0
	v_cndmask_b32_e32 v0, v3, v0, vcc
	v_rsq_f32_e32 v0, v0
	s_nop 0
	v_mul_f32_e32 v3, 0x45800000, v0
	v_cndmask_b32_e32 v0, v0, v3, vcc
	v_mul_f32_e32 v0, v229, v0
	v_mul_f32_e32 v3, v54, v0
	v_mul_f32_e32 v3, v104, v3
	s_nop 1
	v_mov_b32_dpp v4, v3 quad_perm:[1,0,3,2] row_mask:0xf bank_mask:0xf
	s_and_saveexec_b64 s[18:19], s[12:13]
	s_cbranch_execz .LBB0_881
	s_waitcnt lgkmcnt(0)
	v_cvt_pk_bf16_f32 v3, v3, v4
	v_add_co_u32_e32 v4, vcc, 0xa000, v16
	s_nop 1
	v_addc_co_u32_e32 v5, vcc, 0, v17, vcc
	global_store_dword v[4:5], v3, off
.LBB0_881:
	s_or_b64 exec, exec, s[18:19]
	v_mul_f32_e32 v3, v55, v0
	v_mul_f32_e32 v3, v103, v3
	s_waitcnt lgkmcnt(0)
	s_nop 1
	v_mov_b32_dpp v4, v3 quad_perm:[1,0,3,2] row_mask:0xf bank_mask:0xf
	s_and_saveexec_b64 s[18:19], s[12:13]
	s_cbranch_execz .LBB0_883
	s_waitcnt lgkmcnt(0)
	v_cvt_pk_bf16_f32 v3, v3, v4
	v_add_co_u32_e32 v4, vcc, 0xa000, v16
	s_nop 1
	v_addc_co_u32_e32 v5, vcc, 0, v17, vcc
	global_store_dword v[4:5], v3, off offset:64
.LBB0_883:
	s_or_b64 exec, exec, s[18:19]
	v_mul_f32_e32 v3, v68, v0
	v_mul_f32_e32 v3, v105, v3
	s_waitcnt lgkmcnt(0)
	s_nop 1
	v_mov_b32_dpp v4, v3 quad_perm:[1,0,3,2] row_mask:0xf bank_mask:0xf
	s_and_saveexec_b64 s[18:19], s[12:13]
	s_cbranch_execz .LBB0_885
	s_waitcnt lgkmcnt(0)
	v_cvt_pk_bf16_f32 v3, v3, v4
	v_add_co_u32_e32 v4, vcc, 0xa000, v16
	s_nop 1
	v_addc_co_u32_e32 v5, vcc, 0, v17, vcc
	global_store_dword v[4:5], v3, off offset:128
.LBB0_885:
	s_or_b64 exec, exec, s[18:19]
	v_mul_f32_e32 v0, v69, v0
	v_mul_f32_e32 v0, v21, v0
	s_nop 1
	v_mov_b32_dpp v3, v0 quad_perm:[1,0,3,2] row_mask:0xf bank_mask:0xf
	s_and_saveexec_b64 s[18:19], s[12:13]
	s_cbranch_execz .LBB0_887
	s_waitcnt lgkmcnt(1)
	v_add_co_u32_e32 v4, vcc, 0xa000, v16
	s_waitcnt lgkmcnt(0)
	v_cvt_pk_bf16_f32 v0, v0, v3
	v_addc_co_u32_e32 v5, vcc, 0, v17, vcc
	global_store_dword v[4:5], v0, off offset:192
.LBB0_887:
	s_or_b64 exec, exec, s[18:19]
	v_mul_f32_e32 v0, 0x4b800000, v2
	v_cndmask_b32_e64 v0, v2, v0, s[14:15]
	v_rsq_f32_e32 v0, v0
	s_nop 0
	v_mul_f32_e32 v2, 0x45800000, v0
	v_cndmask_b32_e64 v0, v0, v2, s[14:15]
	v_mul_f32_e32 v0, v229, v0
	v_mul_f32_e32 v2, v64, v0
	v_mul_f32_e32 v2, v104, v2
	s_waitcnt lgkmcnt(0)
	s_nop 1
	v_mov_b32_dpp v3, v2 quad_perm:[1,0,3,2] row_mask:0xf bank_mask:0xf
	s_and_saveexec_b64 s[14:15], s[12:13]
	s_cbranch_execz .LBB0_889
	s_waitcnt lgkmcnt(0)
	v_cvt_pk_bf16_f32 v4, v2, v3
	v_add_co_u32_e32 v2, vcc, 0xb000, v16
	s_nop 1
	v_addc_co_u32_e32 v3, vcc, 0, v17, vcc
	global_store_dword v[2:3], v4, off
.LBB0_889:
	s_or_b64 exec, exec, s[14:15]
	v_mul_f32_e32 v2, v65, v0
	v_mul_f32_e32 v2, v103, v2
	s_waitcnt lgkmcnt(0)
	s_nop 1
	v_mov_b32_dpp v3, v2 quad_perm:[1,0,3,2] row_mask:0xf bank_mask:0xf
	s_and_saveexec_b64 s[14:15], s[12:13]
	s_cbranch_execz .LBB0_891
	s_waitcnt lgkmcnt(0)
	v_cvt_pk_bf16_f32 v4, v2, v3
	v_add_co_u32_e32 v2, vcc, 0xb000, v16
	s_nop 1
	v_addc_co_u32_e32 v3, vcc, 0, v17, vcc
	global_store_dword v[2:3], v4, off offset:64
.LBB0_891:
	s_or_b64 exec, exec, s[14:15]
	v_mul_f32_e32 v2, v58, v0
	v_mul_f32_e32 v2, v105, v2
	s_waitcnt lgkmcnt(0)
	s_nop 1
	v_mov_b32_dpp v3, v2 quad_perm:[1,0,3,2] row_mask:0xf bank_mask:0xf
	s_and_saveexec_b64 s[14:15], s[12:13]
	s_cbranch_execz .LBB0_893
	s_waitcnt lgkmcnt(0)
	v_cvt_pk_bf16_f32 v4, v2, v3
	v_add_co_u32_e32 v2, vcc, 0xb000, v16
	s_nop 1
	v_addc_co_u32_e32 v3, vcc, 0, v17, vcc
	global_store_dword v[2:3], v4, off offset:128
.LBB0_893:
	s_or_b64 exec, exec, s[14:15]
	v_mul_f32_e32 v0, v59, v0
	v_mul_f32_e32 v0, v21, v0
	s_nop 1
	v_mov_b32_dpp v2, v0 quad_perm:[1,0,3,2] row_mask:0xf bank_mask:0xf
	s_and_saveexec_b64 s[14:15], s[12:13]
	s_cbranch_execz .LBB0_895
	s_waitcnt lgkmcnt(0)
	v_cvt_pk_bf16_f32 v0, v0, v2
	v_add_co_u32_e32 v2, vcc, 0xb000, v16
	s_nop 1
	v_addc_co_u32_e32 v3, vcc, 0, v17, vcc
	global_store_dword v[2:3], v0, off offset:192
.LBB0_895:
	s_or_b64 exec, exec, s[14:15]
	s_waitcnt lgkmcnt(0)
	v_pk_add_f32 v[2:3], v[72:73], v[74:75]
	s_nop 0
	v_pk_fma_f32 v[2:3], v[2:3], s[2:3], v[198:199] op_sel_hi:[1,0,0]
	s_nop 0
	v_mul_f32_e32 v0, 0x4b800000, v3
	v_cmp_gt_f32_e32 vcc, s16, v3
	v_cmp_gt_f32_e64 s[14:15], s16, v2
	s_nop 0
	v_cndmask_b32_e32 v0, v3, v0, vcc
	v_rsq_f32_e32 v0, v0
	s_nop 0
	v_mul_f32_e32 v3, 0x45800000, v0
	v_cndmask_b32_e32 v0, v0, v3, vcc
	v_mul_f32_e32 v0, v229, v0
	v_mul_f32_e32 v3, v62, v0
	v_mul_f32_e32 v3, v104, v3
	s_nop 1
	v_mov_b32_dpp v4, v3 quad_perm:[1,0,3,2] row_mask:0xf bank_mask:0xf
	s_and_saveexec_b64 s[18:19], s[12:13]
	s_cbranch_execz .LBB0_897
	s_waitcnt lgkmcnt(0)
	v_cvt_pk_bf16_f32 v3, v3, v4
	v_add_co_u32_e32 v4, vcc, 0x10000, v16
	s_nop 1
	v_addc_co_u32_e32 v5, vcc, 0, v17, vcc
	global_store_dword v[4:5], v3, off
.LBB0_897:
	s_or_b64 exec, exec, s[18:19]
	v_mul_f32_e32 v3, v63, v0
	v_mul_f32_e32 v3, v103, v3
	s_waitcnt lgkmcnt(0)
	s_nop 1
	v_mov_b32_dpp v4, v3 quad_perm:[1,0,3,2] row_mask:0xf bank_mask:0xf
	s_and_saveexec_b64 s[18:19], s[12:13]
	s_cbranch_execz .LBB0_899
	s_waitcnt lgkmcnt(0)
	v_cvt_pk_bf16_f32 v3, v3, v4
	v_add_co_u32_e32 v4, vcc, 0x10000, v16
	s_nop 1
	v_addc_co_u32_e32 v5, vcc, 0, v17, vcc
	global_store_dword v[4:5], v3, off offset:64
; __device__ __forceinline__ unsigned cvtpk(float lo, float hi) { const cvt_f32x2 v = {lo, hi}; const cvt_bf16x2 r = __builtin_convertvector(v, cvt_bf16x2); return __builtin_bit_cast(unsigned, r); }
; __device__ __forceinline__ int crow(int r, int hi) { return (r & 3) + 8 * (r >> 2) + 4 * hi; }
; template <int MODE, int VARI>
; __device__ __forceinline__ void attn_unit(LAS unsigned char* lds, const int tid, const AttnP& a, float c2, float lam, const float* subln, float outscale, float fox_u, const bool fast) {
;     ...
;         if (wid < 4) {
;             const float g0 = subln[r32], g1 = subln[32 + r32], g2 = subln[64 + r32], g3 = subln[96 + r32];
; #pragma unroll
;             for (int r = 0; r < 16; ++r) {
;                 float v[4]; float ss = 0.f;
; #pragma unroll
;                 for (int d = 0; d < 4; ++d) { v[d] = o[d][r] - lam * X[(d * 16 + r) * 64]; ss += v[d] * v[d]; }
;                 ss += __shfl_xor(ss, 1); ss += __shfl_xor(ss, 2); ss += __shfl_xor(ss, 4); ss += __shfl_xor(ss, 8); ss += __shfl_xor(ss, 16);
;                 const float rs = rsqrtf(ss * (1.0f / 128.0f) + RMS_EPS) * outscale;
;                 o[0][r] = v[0] * rs * g0; o[1][r] = v[1] * rs * g1; o[2][r] = v[2] * rs * g2; o[3][r] = v[3] * rs * g3;
;             }
;     ...
;     if (WIDE || wid < 4) {
;         bf16_t* Ow = a.O + (size_t)qpos0 * 2048;
; #pragma unroll
;         for (int r = 0; r < 16; ++r) { const int orow = crow(r, hi);
; #pragma unroll
;             for (int d = 0; d < 4; ++d) { const float v = o[d][r]; const float vn = __shfl_xor(v, 1);
;                 if ((r32 & 1) == 0) *(unsigned*)(Ow + (size_t)orow * 2048 + d * 32 + r32) = cvtpk(v, vn); } }
;     }
.LBB0_899:
	s_or_b64 exec, exec, s[18:19]
	v_mul_f32_e32 v3, v52, v0
	v_mul_f32_e32 v3, v105, v3
	s_waitcnt lgkmcnt(0)
	s_nop 1
	v_mov_b32_dpp v4, v3 quad_perm:[1,0,3,2] row_mask:0xf bank_mask:0xf
	s_and_saveexec_b64 s[18:19], s[12:13]
	s_cbranch_execz .LBB0_901
	s_waitcnt lgkmcnt(0)
	v_cvt_pk_bf16_f32 v3, v3, v4
	v_add_co_u32_e32 v4, vcc, 0x10000, v16
	s_nop 1
	v_addc_co_u32_e32 v5, vcc, 0, v17, vcc
	global_store_dword v[4:5], v3, off offset:128
.LBB0_901:
	s_or_b64 exec, exec, s[18:19]
	v_mul_f32_e32 v0, v53, v0
	v_mul_f32_e32 v0, v21, v0
	s_nop 1
	v_mov_b32_dpp v3, v0 quad_perm:[1,0,3,2] row_mask:0xf bank_mask:0xf
	s_and_saveexec_b64 s[18:19], s[12:13]
	s_cbranch_execz .LBB0_903
	s_waitcnt lgkmcnt(1)
	v_add_co_u32_e32 v4, vcc, 0x10000, v16
	s_waitcnt lgkmcnt(0)
	v_cvt_pk_bf16_f32 v0, v0, v3
	v_addc_co_u32_e32 v5, vcc, 0, v17, vcc
	global_store_dword v[4:5], v0, off offset:192
.LBB0_903:
	s_or_b64 exec, exec, s[18:19]
	v_mul_f32_e32 v0, 0x4b800000, v2
	v_cndmask_b32_e64 v0, v2, v0, s[14:15]
	v_rsq_f32_e32 v0, v0
	s_nop 0
	v_mul_f32_e32 v2, 0x45800000, v0
	v_cndmask_b32_e64 v0, v0, v2, s[14:15]
	v_mul_f32_e32 v0, v229, v0
	v_mul_f32_e32 v2, v46, v0
	v_mul_f32_e32 v2, v104, v2
	s_waitcnt lgkmcnt(0)
	s_nop 1
	v_mov_b32_dpp v3, v2 quad_perm:[1,0,3,2] row_mask:0xf bank_mask:0xf
	s_and_saveexec_b64 s[14:15], s[12:13]
	s_cbranch_execz .LBB0_905
	s_waitcnt lgkmcnt(0)
	v_cvt_pk_bf16_f32 v4, v2, v3
	v_add_co_u32_e32 v2, vcc, 0x11000, v16
	s_nop 1
	v_addc_co_u32_e32 v3, vcc, 0, v17, vcc
	global_store_dword v[2:3], v4, off
.LBB0_905:
	s_or_b64 exec, exec, s[14:15]
	v_mul_f32_e32 v2, v47, v0
	v_mul_f32_e32 v2, v103, v2
	s_waitcnt lgkmcnt(0)
	s_nop 1
	v_mov_b32_dpp v3, v2 quad_perm:[1,0,3,2] row_mask:0xf bank_mask:0xf
	s_and_saveexec_b64 s[14:15], s[12:13]
	s_cbranch_execz .LBB0_907
	s_waitcnt lgkmcnt(0)
	v_cvt_pk_bf16_f32 v4, v2, v3
	v_add_co_u32_e32 v2, vcc, 0x11000, v16
	s_nop 1
	v_addc_co_u32_e32 v3, vcc, 0, v17, vcc
	global_store_dword v[2:3], v4, off offset:64
.LBB0_907:
	s_or_b64 exec, exec, s[14:15]
	v_mul_f32_e32 v2, v40, v0
	v_mul_f32_e32 v2, v105, v2
	s_waitcnt lgkmcnt(0)
	s_nop 1
	v_mov_b32_dpp v3, v2 quad_perm:[1,0,3,2] row_mask:0xf bank_mask:0xf
	s_and_saveexec_b64 s[14:15], s[12:13]
	s_cbranch_execz .LBB0_909
	s_waitcnt lgkmcnt(0)
	v_cvt_pk_bf16_f32 v4, v2, v3
	v_add_co_u32_e32 v2, vcc, 0x11000, v16
	s_nop 1
	v_addc_co_u32_e32 v3, vcc, 0, v17, vcc
	global_store_dword v[2:3], v4, off offset:128
.LBB0_909:
	s_or_b64 exec, exec, s[14:15]
	v_mul_f32_e32 v0, v41, v0
	v_mul_f32_e32 v0, v21, v0
	s_nop 1
	v_mov_b32_dpp v2, v0 quad_perm:[1,0,3,2] row_mask:0xf bank_mask:0xf
	s_and_saveexec_b64 s[14:15], s[12:13]
	s_cbranch_execz .LBB0_911
	s_waitcnt lgkmcnt(0)
	v_cvt_pk_bf16_f32 v0, v0, v2
	v_add_co_u32_e32 v2, vcc, 0x11000, v16
	s_nop 1
	v_addc_co_u32_e32 v3, vcc, 0, v17, vcc
	global_store_dword v[2:3], v0, off offset:192
.LBB0_911:
	s_or_b64 exec, exec, s[14:15]
	s_waitcnt lgkmcnt(0)
	v_pk_add_f32 v[2:3], v[94:95], v[96:97]
	s_nop 0
	v_pk_fma_f32 v[2:3], v[2:3], s[2:3], v[198:199] op_sel_hi:[1,0,0]
	s_nop 0
	v_mul_f32_e32 v0, 0x4b800000, v3
	v_cmp_gt_f32_e32 vcc, s16, v3
	v_cmp_gt_f32_e64 s[14:15], s16, v2
	s_nop 0
	v_cndmask_b32_e32 v0, v3, v0, vcc
	v_rsq_f32_e32 v0, v0
	s_nop 0
	v_mul_f32_e32 v3, 0x45800000, v0
	v_cndmask_b32_e32 v0, v0, v3, vcc
	v_mul_f32_e32 v0, v229, v0
	v_mul_f32_e32 v3, v56, v0
	v_mul_f32_e32 v3, v104, v3
	s_nop 1
	v_mov_b32_dpp v4, v3 quad_perm:[1,0,3,2] row_mask:0xf bank_mask:0xf
	s_and_saveexec_b64 s[18:19], s[12:13]
	s_cbranch_execz .LBB0_913
	s_waitcnt lgkmcnt(0)
	v_cvt_pk_bf16_f32 v3, v3, v4
	v_add_co_u32_e32 v4, vcc, 0x12000, v16
	s_nop 1
	v_addc_co_u32_e32 v5, vcc, 0, v17, vcc
	global_store_dword v[4:5], v3, off
.LBB0_913:
	s_or_b64 exec, exec, s[18:19]
	v_mul_f32_e32 v3, v57, v0
	v_mul_f32_e32 v3, v103, v3
	s_waitcnt lgkmcnt(0)
	s_nop 1
	v_mov_b32_dpp v4, v3 quad_perm:[1,0,3,2] row_mask:0xf bank_mask:0xf
	s_and_saveexec_b64 s[18:19], s[12:13]
	s_cbranch_execz .LBB0_915
	s_waitcnt lgkmcnt(0)
	v_cvt_pk_bf16_f32 v3, v3, v4
	v_add_co_u32_e32 v4, vcc, 0x12000, v16
	s_nop 1
	v_addc_co_u32_e32 v5, vcc, 0, v17, vcc
	global_store_dword v[4:5], v3, off offset:64
.LBB0_915:
	s_or_b64 exec, exec, s[18:19]
	v_mul_f32_e32 v3, v48, v0
	v_mul_f32_e32 v3, v105, v3
	s_waitcnt lgkmcnt(0)
	s_nop 1
	v_mov_b32_dpp v4, v3 quad_perm:[1,0,3,2] row_mask:0xf bank_mask:0xf
	s_and_saveexec_b64 s[18:19], s[12:13]
	s_cbranch_execz .LBB0_917
	s_waitcnt lgkmcnt(0)
	v_cvt_pk_bf16_f32 v3, v3, v4
	v_add_co_u32_e32 v4, vcc, 0x12000, v16
	s_nop 1
	v_addc_co_u32_e32 v5, vcc, 0, v17, vcc
	global_store_dword v[4:5], v3, off offset:128
.LBB0_917:
	s_or_b64 exec, exec, s[18:19]
	v_mul_f32_e32 v0, v49, v0
	v_mul_f32_e32 v0, v21, v0
	s_nop 1
	v_mov_b32_dpp v3, v0 quad_perm:[1,0,3,2] row_mask:0xf bank_mask:0xf
	s_and_saveexec_b64 s[18:19], s[12:13]
	s_cbranch_execz .LBB0_919
	s_waitcnt lgkmcnt(1)
	v_add_co_u32_e32 v4, vcc, 0x12000, v16
	s_waitcnt lgkmcnt(0)
	v_cvt_pk_bf16_f32 v0, v0, v3
	v_addc_co_u32_e32 v5, vcc, 0, v17, vcc
	global_store_dword v[4:5], v0, off offset:192
.LBB0_919:
	s_or_b64 exec, exec, s[18:19]
	v_mul_f32_e32 v0, 0x4b800000, v2
	v_cndmask_b32_e64 v0, v2, v0, s[14:15]
	v_rsq_f32_e32 v0, v0
	s_nop 0
	v_mul_f32_e32 v2, 0x45800000, v0
	v_cndmask_b32_e64 v0, v0, v2, s[14:15]
	v_mul_f32_e32 v0, v229, v0
	v_mul_f32_e32 v2, v42, v0
	v_mul_f32_e32 v2, v104, v2
	s_waitcnt lgkmcnt(0)
	s_nop 1
	v_mov_b32_dpp v3, v2 quad_perm:[1,0,3,2] row_mask:0xf bank_mask:0xf
	s_and_saveexec_b64 s[14:15], s[12:13]
	s_cbranch_execz .LBB0_921
	s_waitcnt lgkmcnt(0)
	v_cvt_pk_bf16_f32 v4, v2, v3
	v_add_co_u32_e32 v2, vcc, 0x13000, v16
	s_nop 1
	v_addc_co_u32_e32 v3, vcc, 0, v17, vcc
	global_store_dword v[2:3], v4, off
; __device__ __forceinline__ unsigned cvtpk(float lo, float hi) { const cvt_f32x2 v = {lo, hi}; const cvt_bf16x2 r = __builtin_convertvector(v, cvt_bf16x2); return __builtin_bit_cast(unsigned, r); }
; __device__ __forceinline__ int crow(int r, int hi) { return (r & 3) + 8 * (r >> 2) + 4 * hi; }
; template <int MODE, int VARI>
; __device__ __forceinline__ void attn_unit(LAS unsigned char* lds, const int tid, const AttnP& a, float c2, float lam, const float* subln, float outscale, float fox_u, const bool fast) {
;     ...
;         if (wid < 4) {
;             const float g0 = subln[r32], g1 = subln[32 + r32], g2 = subln[64 + r32], g3 = subln[96 + r32];
; #pragma unroll
;             for (int r = 0; r < 16; ++r) {
;                 float v[4]; float ss = 0.f;
; #pragma unroll
;                 for (int d = 0; d < 4; ++d) { v[d] = o[d][r] - lam * X[(d * 16 + r) * 64]; ss += v[d] * v[d]; }
;                 ss += __shfl_xor(ss, 1); ss += __shfl_xor(ss, 2); ss += __shfl_xor(ss, 4); ss += __shfl_xor(ss, 8); ss += __shfl_xor(ss, 16);
;                 const float rs = rsqrtf(ss * (1.0f / 128.0f) + RMS_EPS) * outscale;
;                 o[0][r] = v[0] * rs * g0; o[1][r] = v[1] * rs * g1; o[2][r] = v[2] * rs * g2; o[3][r] = v[3] * rs * g3;
;             }
;     ...
;     if (WIDE || wid < 4) {
;         bf16_t* Ow = a.O + (size_t)qpos0 * 2048;
; #pragma unroll
;         for (int r = 0; r < 16; ++r) { const int orow = crow(r, hi);
; #pragma unroll
;             for (int d = 0; d < 4; ++d) { const float v = o[d][r]; const float vn = __shfl_xor(v, 1);
;                 if ((r32 & 1) == 0) *(unsigned*)(Ow + (size_t)orow * 2048 + d * 32 + r32) = cvtpk(v, vn); } }
;     }
.LBB0_921:
	s_or_b64 exec, exec, s[14:15]
	v_mul_f32_e32 v2, v43, v0
	v_mul_f32_e32 v2, v103, v2
	s_waitcnt lgkmcnt(0)
	s_nop 1
	v_mov_b32_dpp v3, v2 quad_perm:[1,0,3,2] row_mask:0xf bank_mask:0xf
	s_and_saveexec_b64 s[14:15], s[12:13]
	s_cbranch_execz .LBB0_923
	s_waitcnt lgkmcnt(0)
	v_cvt_pk_bf16_f32 v4, v2, v3
	v_add_co_u32_e32 v2, vcc, 0x13000, v16
	s_nop 1
	v_addc_co_u32_e32 v3, vcc, 0, v17, vcc
	global_store_dword v[2:3], v4, off offset:64
.LBB0_923:
	s_or_b64 exec, exec, s[14:15]
	v_mul_f32_e32 v2, v36, v0
	v_mul_f32_e32 v2, v105, v2
	s_waitcnt lgkmcnt(0)
	s_nop 1
	v_mov_b32_dpp v3, v2 quad_perm:[1,0,3,2] row_mask:0xf bank_mask:0xf
	s_and_saveexec_b64 s[14:15], s[12:13]
	s_cbranch_execz .LBB0_925
	s_waitcnt lgkmcnt(0)
	v_cvt_pk_bf16_f32 v4, v2, v3
	v_add_co_u32_e32 v2, vcc, 0x13000, v16
	s_nop 1
	v_addc_co_u32_e32 v3, vcc, 0, v17, vcc
	global_store_dword v[2:3], v4, off offset:128
.LBB0_925:
	s_or_b64 exec, exec, s[14:15]
	v_mul_f32_e32 v0, v37, v0
	v_mul_f32_e32 v0, v21, v0
	s_nop 1
	v_mov_b32_dpp v2, v0 quad_perm:[1,0,3,2] row_mask:0xf bank_mask:0xf
	s_and_saveexec_b64 s[14:15], s[12:13]
	s_cbranch_execz .LBB0_927
	s_waitcnt lgkmcnt(0)
	v_cvt_pk_bf16_f32 v0, v0, v2
	v_add_co_u32_e32 v2, vcc, 0x13000, v16
	s_nop 1
	v_addc_co_u32_e32 v3, vcc, 0, v17, vcc
	global_store_dword v[2:3], v0, off offset:192
.LBB0_927:
	s_or_b64 exec, exec, s[14:15]
	s_waitcnt lgkmcnt(0)
	v_pk_add_f32 v[2:3], v[90:91], v[92:93]
	s_nop 0
	v_pk_fma_f32 v[2:3], v[2:3], s[2:3], v[198:199] op_sel_hi:[1,0,0]
	s_nop 0
	v_mul_f32_e32 v0, 0x4b800000, v3
	v_cmp_gt_f32_e32 vcc, s16, v3
	v_cmp_gt_f32_e64 s[14:15], s16, v2
	s_nop 0
	v_cndmask_b32_e32 v0, v3, v0, vcc
	v_rsq_f32_e32 v0, v0
	s_nop 0
	v_mul_f32_e32 v3, 0x45800000, v0
	v_cndmask_b32_e32 v0, v0, v3, vcc
	v_mul_f32_e32 v0, v229, v0
	v_mul_f32_e32 v3, v60, v0
	v_mul_f32_e32 v3, v104, v3
	s_nop 1
	v_mov_b32_dpp v4, v3 quad_perm:[1,0,3,2] row_mask:0xf bank_mask:0xf
	s_and_saveexec_b64 s[18:19], s[12:13]
	s_cbranch_execz .LBB0_929
	s_waitcnt lgkmcnt(0)
	v_cvt_pk_bf16_f32 v3, v3, v4
	v_add_co_u32_e32 v4, vcc, 0x18000, v16
	s_nop 1
	v_addc_co_u32_e32 v5, vcc, 0, v17, vcc
	global_store_dword v[4:5], v3, off
.LBB0_929:
	s_or_b64 exec, exec, s[18:19]
	v_mul_f32_e32 v3, v61, v0
	v_mul_f32_e32 v3, v103, v3
	s_waitcnt lgkmcnt(0)
	s_nop 1
	v_mov_b32_dpp v4, v3 quad_perm:[1,0,3,2] row_mask:0xf bank_mask:0xf
	s_and_saveexec_b64 s[18:19], s[12:13]
	s_cbranch_execz .LBB0_931
	s_waitcnt lgkmcnt(0)
	v_cvt_pk_bf16_f32 v3, v3, v4
	v_add_co_u32_e32 v4, vcc, 0x18000, v16
	s_nop 1
	v_addc_co_u32_e32 v5, vcc, 0, v17, vcc
	global_store_dword v[4:5], v3, off offset:64
.LBB0_931:
	s_or_b64 exec, exec, s[18:19]
	v_mul_f32_e32 v3, v50, v0
	v_mul_f32_e32 v3, v105, v3
	s_waitcnt lgkmcnt(0)
	s_nop 1
	v_mov_b32_dpp v4, v3 quad_perm:[1,0,3,2] row_mask:0xf bank_mask:0xf
	s_and_saveexec_b64 s[18:19], s[12:13]
	s_cbranch_execz .LBB0_933
	s_waitcnt lgkmcnt(0)
	v_cvt_pk_bf16_f32 v3, v3, v4
	v_add_co_u32_e32 v4, vcc, 0x18000, v16
	s_nop 1
	v_addc_co_u32_e32 v5, vcc, 0, v17, vcc
	global_store_dword v[4:5], v3, off offset:128
.LBB0_933:
	s_or_b64 exec, exec, s[18:19]
	v_mul_f32_e32 v0, v51, v0
	v_mul_f32_e32 v0, v21, v0
	s_nop 1
	v_mov_b32_dpp v3, v0 quad_perm:[1,0,3,2] row_mask:0xf bank_mask:0xf
	s_and_saveexec_b64 s[18:19], s[12:13]
	s_cbranch_execz .LBB0_935
	s_waitcnt lgkmcnt(1)
	v_add_co_u32_e32 v4, vcc, 0x18000, v16
	s_waitcnt lgkmcnt(0)
	v_cvt_pk_bf16_f32 v0, v0, v3
	v_addc_co_u32_e32 v5, vcc, 0, v17, vcc
	global_store_dword v[4:5], v0, off offset:192
.LBB0_935:
	s_or_b64 exec, exec, s[18:19]
	v_mul_f32_e32 v0, 0x4b800000, v2
	v_cndmask_b32_e64 v0, v2, v0, s[14:15]
	v_rsq_f32_e32 v0, v0
	s_nop 0
	v_mul_f32_e32 v2, 0x45800000, v0
	v_cndmask_b32_e64 v0, v0, v2, s[14:15]
	v_mul_f32_e32 v0, v229, v0
	v_mul_f32_e32 v2, v44, v0
	v_mul_f32_e32 v2, v104, v2
	s_waitcnt lgkmcnt(0)
	s_nop 1
	v_mov_b32_dpp v3, v2 quad_perm:[1,0,3,2] row_mask:0xf bank_mask:0xf
	s_and_saveexec_b64 s[14:15], s[12:13]
	s_cbranch_execz .LBB0_937
	s_waitcnt lgkmcnt(0)
	v_cvt_pk_bf16_f32 v4, v2, v3
	v_add_co_u32_e32 v2, vcc, 0x19000, v16
	s_nop 1
	v_addc_co_u32_e32 v3, vcc, 0, v17, vcc
	global_store_dword v[2:3], v4, off
.LBB0_937:
	s_or_b64 exec, exec, s[14:15]
	v_mul_f32_e32 v2, v45, v0
	v_mul_f32_e32 v2, v103, v2
	s_waitcnt lgkmcnt(0)
	s_nop 1
	v_mov_b32_dpp v3, v2 quad_perm:[1,0,3,2] row_mask:0xf bank_mask:0xf
	s_and_saveexec_b64 s[14:15], s[12:13]
	s_cbranch_execz .LBB0_939
	s_waitcnt lgkmcnt(0)
	v_cvt_pk_bf16_f32 v4, v2, v3
	v_add_co_u32_e32 v2, vcc, 0x19000, v16
	s_nop 1
	v_addc_co_u32_e32 v3, vcc, 0, v17, vcc
	global_store_dword v[2:3], v4, off offset:64
; __device__ __forceinline__ unsigned cvtpk(float lo, float hi) { const cvt_f32x2 v = {lo, hi}; const cvt_bf16x2 r = __builtin_convertvector(v, cvt_bf16x2); return __builtin_bit_cast(unsigned, r); }
; __device__ __forceinline__ int crow(int r, int hi) { return (r & 3) + 8 * (r >> 2) + 4 * hi; }
; template <int MODE, int VARI>
; __device__ __forceinline__ void attn_unit(LAS unsigned char* lds, const int tid, const AttnP& a, float c2, float lam, const float* subln, float outscale, float fox_u, const bool fast) {
;     ...
;         if (wid < 4) {
;             const float g0 = subln[r32], g1 = subln[32 + r32], g2 = subln[64 + r32], g3 = subln[96 + r32];
; #pragma unroll
;             for (int r = 0; r < 16; ++r) {
;                 float v[4]; float ss = 0.f;
; #pragma unroll
;                 for (int d = 0; d < 4; ++d) { v[d] = o[d][r] - lam * X[(d * 16 + r) * 64]; ss += v[d] * v[d]; }
;                 ss += __shfl_xor(ss, 1); ss += __shfl_xor(ss, 2); ss += __shfl_xor(ss, 4); ss += __shfl_xor(ss, 8); ss += __shfl_xor(ss, 16);
;                 const float rs = rsqrtf(ss * (1.0f / 128.0f) + RMS_EPS) * outscale;
;                 o[0][r] = v[0] * rs * g0; o[1][r] = v[1] * rs * g1; o[2][r] = v[2] * rs * g2; o[3][r] = v[3] * rs * g3;
;             }
;     ...
;     if (WIDE || wid < 4) {
;         bf16_t* Ow = a.O + (size_t)qpos0 * 2048;
; #pragma unroll
;         for (int r = 0; r < 16; ++r) { const int orow = crow(r, hi);
; #pragma unroll
;             for (int d = 0; d < 4; ++d) { const float v = o[d][r]; const float vn = __shfl_xor(v, 1);
;                 if ((r32 & 1) == 0) *(unsigned*)(Ow + (size_t)orow * 2048 + d * 32 + r32) = cvtpk(v, vn); } }
;     }
.LBB0_939:
	s_or_b64 exec, exec, s[14:15]
	v_mul_f32_e32 v2, v38, v0
	v_mul_f32_e32 v2, v105, v2
	s_waitcnt lgkmcnt(0)
	s_nop 1
	v_mov_b32_dpp v3, v2 quad_perm:[1,0,3,2] row_mask:0xf bank_mask:0xf
	s_and_saveexec_b64 s[14:15], s[12:13]
	s_cbranch_execz .LBB0_941
	s_waitcnt lgkmcnt(0)
	v_cvt_pk_bf16_f32 v4, v2, v3
	v_add_co_u32_e32 v2, vcc, 0x19000, v16
	s_nop 1
	v_addc_co_u32_e32 v3, vcc, 0, v17, vcc
	global_store_dword v[2:3], v4, off offset:128
.LBB0_941:
	s_or_b64 exec, exec, s[14:15]
	v_mul_f32_e32 v0, v39, v0
	v_mul_f32_e32 v0, v21, v0
	s_nop 1
	v_mov_b32_dpp v2, v0 quad_perm:[1,0,3,2] row_mask:0xf bank_mask:0xf
	s_and_saveexec_b64 s[14:15], s[12:13]
	s_cbranch_execz .LBB0_943
	s_waitcnt lgkmcnt(0)
	v_cvt_pk_bf16_f32 v0, v0, v2
	v_add_co_u32_e32 v2, vcc, 0x19000, v16
	s_nop 1
	v_addc_co_u32_e32 v3, vcc, 0, v17, vcc
	global_store_dword v[2:3], v0, off offset:192
.LBB0_943:
	s_or_b64 exec, exec, s[14:15]
	s_waitcnt lgkmcnt(0)
	v_pk_add_f32 v[2:3], v[70:71], v[82:83]
	s_nop 0
	v_pk_fma_f32 v[2:3], v[2:3], s[2:3], v[198:199] op_sel_hi:[1,0,0]
	s_nop 0
	v_mul_f32_e32 v0, 0x4b800000, v3
	v_cmp_gt_f32_e32 vcc, s16, v3
	v_cmp_gt_f32_e64 s[14:15], s16, v2
	s_nop 0
	v_cndmask_b32_e32 v0, v3, v0, vcc
	v_rsq_f32_e32 v0, v0
	s_nop 0
	v_mul_f32_e32 v3, 0x45800000, v0
	v_cndmask_b32_e32 v0, v0, v3, vcc
	v_mul_f32_e32 v0, v229, v0
	v_mul_f32_e32 v3, v30, v0
	v_mul_f32_e32 v3, v104, v3
	s_nop 1
	v_mov_b32_dpp v4, v3 quad_perm:[1,0,3,2] row_mask:0xf bank_mask:0xf
	s_and_saveexec_b64 s[18:19], s[12:13]
	s_cbranch_execz .LBB0_945
	s_waitcnt lgkmcnt(0)
	v_cvt_pk_bf16_f32 v3, v3, v4
	v_add_co_u32_e32 v4, vcc, 0x1a000, v16
	s_nop 1
	v_addc_co_u32_e32 v5, vcc, 0, v17, vcc
	global_store_dword v[4:5], v3, off
.LBB0_945:
	s_or_b64 exec, exec, s[18:19]
	v_mul_f32_e32 v3, v31, v0
	v_mul_f32_e32 v3, v103, v3
	s_waitcnt lgkmcnt(0)
	s_nop 1
	v_mov_b32_dpp v4, v3 quad_perm:[1,0,3,2] row_mask:0xf bank_mask:0xf
	s_and_saveexec_b64 s[18:19], s[12:13]
	s_cbranch_execz .LBB0_947
	s_waitcnt lgkmcnt(0)
	v_cvt_pk_bf16_f32 v3, v3, v4
	v_add_co_u32_e32 v4, vcc, 0x1a000, v16
	s_nop 1
	v_addc_co_u32_e32 v5, vcc, 0, v17, vcc
	global_store_dword v[4:5], v3, off offset:64
.LBB0_947:
	s_or_b64 exec, exec, s[18:19]
	v_mul_f32_e32 v3, v66, v0
	v_mul_f32_e32 v3, v105, v3
	s_waitcnt lgkmcnt(0)
	s_nop 1
	v_mov_b32_dpp v4, v3 quad_perm:[1,0,3,2] row_mask:0xf bank_mask:0xf
	s_and_saveexec_b64 s[18:19], s[12:13]
	s_cbranch_execz .LBB0_949
	s_waitcnt lgkmcnt(0)
	v_cvt_pk_bf16_f32 v3, v3, v4
	v_add_co_u32_e32 v4, vcc, 0x1a000, v16
	s_nop 1
	v_addc_co_u32_e32 v5, vcc, 0, v17, vcc
	global_store_dword v[4:5], v3, off offset:128
.LBB0_949:
	s_or_b64 exec, exec, s[18:19]
	v_mul_f32_e32 v0, v67, v0
	v_mul_f32_e32 v0, v21, v0
	s_nop 1
	v_mov_b32_dpp v3, v0 quad_perm:[1,0,3,2] row_mask:0xf bank_mask:0xf
	s_and_saveexec_b64 s[18:19], s[12:13]
	s_cbranch_execz .LBB0_951
	s_waitcnt lgkmcnt(1)
	v_add_co_u32_e32 v4, vcc, 0x1a000, v16
	s_waitcnt lgkmcnt(0)
	v_cvt_pk_bf16_f32 v0, v0, v3
	v_addc_co_u32_e32 v5, vcc, 0, v17, vcc
	global_store_dword v[4:5], v0, off offset:192
.LBB0_951:
	s_or_b64 exec, exec, s[18:19]
	v_mul_f32_e32 v0, 0x4b800000, v2
	v_cndmask_b32_e64 v0, v2, v0, s[14:15]
	v_rsq_f32_e32 v0, v0
	s_nop 0
	v_mul_f32_e32 v2, 0x45800000, v0
	v_cndmask_b32_e64 v0, v0, v2, s[14:15]
	v_mul_f32_e32 v0, v229, v0
	v_mul_f32_e32 v2, v14, v0
	v_mul_f32_e32 v2, v104, v2
	s_waitcnt lgkmcnt(0)
	s_nop 1
	v_mov_b32_dpp v3, v2 quad_perm:[1,0,3,2] row_mask:0xf bank_mask:0xf
	s_and_saveexec_b64 s[14:15], s[12:13]
	s_cbranch_execz .LBB0_953
	s_waitcnt lgkmcnt(0)
	v_cvt_pk_bf16_f32 v4, v2, v3
	v_add_co_u32_e32 v2, vcc, 0x1b000, v16
	s_nop 1
	v_addc_co_u32_e32 v3, vcc, 0, v17, vcc
	global_store_dword v[2:3], v4, off
.LBB0_953:
	s_or_b64 exec, exec, s[14:15]
	v_mul_f32_e32 v2, v15, v0
	v_mul_f32_e32 v2, v103, v2
	s_waitcnt lgkmcnt(0)
	s_nop 1
	v_mov_b32_dpp v3, v2 quad_perm:[1,0,3,2] row_mask:0xf bank_mask:0xf
	s_and_saveexec_b64 s[14:15], s[12:13]
	s_cbranch_execz .LBB0_955
	s_waitcnt lgkmcnt(0)
	v_cvt_pk_bf16_f32 v4, v2, v3
	v_add_co_u32_e32 v2, vcc, 0x1b000, v16
	s_nop 1
	v_addc_co_u32_e32 v3, vcc, 0, v17, vcc
	global_store_dword v[2:3], v4, off offset:64
.LBB0_955:
	s_or_b64 exec, exec, s[14:15]
	v_mul_f32_e32 v2, v12, v0
	v_mul_f32_e32 v2, v105, v2
	s_waitcnt lgkmcnt(0)
	s_nop 1
	v_mov_b32_dpp v3, v2 quad_perm:[1,0,3,2] row_mask:0xf bank_mask:0xf
	s_and_saveexec_b64 s[14:15], s[12:13]
	s_cbranch_execz .LBB0_957
	s_waitcnt lgkmcnt(0)
	v_cvt_pk_bf16_f32 v4, v2, v3
	v_add_co_u32_e32 v2, vcc, 0x1b000, v16
	s_nop 1
	v_addc_co_u32_e32 v3, vcc, 0, v17, vcc
	global_store_dword v[2:3], v4, off offset:128
.LBB0_957:
	s_or_b64 exec, exec, s[14:15]
	v_mul_f32_e32 v0, v13, v0
	v_mul_f32_e32 v0, v21, v0
	s_nop 1
	v_mov_b32_dpp v2, v0 quad_perm:[1,0,3,2] row_mask:0xf bank_mask:0xf
	s_and_saveexec_b64 s[14:15], s[12:13]
	s_cbranch_execz .LBB0_562
	s_waitcnt lgkmcnt(0)
	v_cvt_pk_bf16_f32 v0, v0, v2
	v_add_co_u32_e32 v2, vcc, 0x1b000, v16
	s_nop 1
	v_addc_co_u32_e32 v3, vcc, 0, v17, vcc
	global_store_dword v[2:3], v0, off offset:192
	s_branch .LBB0_562

; __device__ __forceinline__ unsigned cvtpk(float lo, float hi) { const cvt_f32x2 v = {lo, hi}; const cvt_bf16x2 r = __builtin_convertvector(v, cvt_bf16x2); return __builtin_bit_cast(unsigned, r); }
; __device__ __forceinline__ int crow(int r, int hi) { return (r & 3) + 8 * (r >> 2) + 4 * hi; }
; template <int MODE, int VARI>
; __device__ __forceinline__ void attn_unit(LAS unsigned char* lds, const int tid, const AttnP& a, float c2, float lam, const float* subln, float outscale, float fox_u, const bool fast) {
;     ...
;     } else if (WIDE) {
;         if (hi == 0) li_l[r32] = l_reg;
;         asm volatile("s_waitcnt lgkmcnt(0)" ::: "memory");
; #pragma unroll
;         for (int r = 0; r < 16; ++r) { const float rl = __builtin_amdgcn_rcpf(li_l[crow(r, hi)]);
; #pragma unroll
;             for (int d = 0; d < 4; ++d) o[d][r] *= rl; }
;     ...
;     if (WIDE || wid < 4) {
;         bf16_t* Ow = a.O + (size_t)qpos0 * 2048;
; #pragma unroll
;         for (int r = 0; r < 16; ++r) { const int orow = crow(r, hi);
; #pragma unroll
;             for (int d = 0; d < 4; ++d) { const float v = o[d][r]; const float vn = __shfl_xor(v, 1);
;                 if ((r32 & 1) == 0) *(unsigned*)(Ow + (size_t)orow * 2048 + d * 32 + r32) = cvtpk(v, vn); } }
;     }
.LBB0_980:
	s_waitcnt vmcnt(0)
	v_cmp_gt_u32_e32 vcc, 32, v177
	s_waitcnt vmcnt(0)
	s_barrier
	s_and_saveexec_b64 s[12:13], vcc
	s_mov_b32 s60, 0x2c000
	v_lshl_add_u32 v0, v184, 2, s77
	ds_write_b32 v0, v80
	s_or_b64 exec, exec, s[12:13]
	s_waitcnt lgkmcnt(0)
	v_add_u32_e32 v0, s77, v176
	ds_read_b128 v[112:115], v0
	ds_read_b128 v[116:119], v0 offset:32
	ds_read_b128 v[120:123], v0 offset:64
	ds_read_b128 v[124:127], v0 offset:96
	v_readlane_b32 s2, v255, 27
	s_nop 1
	s_add_u32 s2, s2, s11
	v_readlane_b32 s6, v255, 28
	s_nop 1
	s_addc_u32 s8, s6, 0
	s_ashr_i32 s77, s76, 31
	s_lshl_b64 s[6:7], s[76:77], 12
	s_add_u32 s6, s2, s6
	s_addc_u32 s7, s8, s7
	v_lshlrev_b32_e32 v14, 1, v184
	v_lshl_add_u32 v14, v185, 14, v14
	v_and_b32_e32 v0, 1, v230
	v_cmp_eq_u32_e64 s[12:13], 0, v0
	s_waitcnt lgkmcnt(0)
	v_rcp_f32_e32 v112, v112
	v_rcp_f32_e32 v113, v113
	v_rcp_f32_e32 v114, v114
	v_rcp_f32_e32 v115, v115
	v_rcp_f32_e32 v116, v116
	v_rcp_f32_e32 v117, v117
	v_rcp_f32_e32 v118, v118
	v_rcp_f32_e32 v119, v119
	v_rcp_f32_e32 v120, v120
	v_rcp_f32_e32 v121, v121
	v_rcp_f32_e32 v122, v122
	v_rcp_f32_e32 v123, v123
	v_rcp_f32_e32 v124, v124
	v_rcp_f32_e32 v125, v125
	v_rcp_f32_e32 v126, v126
	v_rcp_f32_e32 v127, v127
	s_nop 0
	v_pk_mul_f32 v[64:65], v[64:65], v[112:113]
	v_pk_mul_f32 v[66:67], v[66:67], v[114:115]
	v_pk_mul_f32 v[68:69], v[68:69], v[116:117]
	v_pk_mul_f32 v[70:71], v[70:71], v[118:119]
	v_pk_mul_f32 v[72:73], v[72:73], v[120:121]
	v_pk_mul_f32 v[74:75], v[74:75], v[122:123]
	v_pk_mul_f32 v[76:77], v[76:77], v[124:125]
	v_pk_mul_f32 v[78:79], v[78:79], v[126:127]
	v_pk_mul_f32 v[48:49], v[48:49], v[112:113]
	v_pk_mul_f32 v[50:51], v[50:51], v[114:115]
	v_pk_mul_f32 v[52:53], v[52:53], v[116:117]
	v_pk_mul_f32 v[54:55], v[54:55], v[118:119]
	v_pk_mul_f32 v[56:57], v[56:57], v[120:121]
	v_pk_mul_f32 v[58:59], v[58:59], v[122:123]
	v_pk_mul_f32 v[60:61], v[60:61], v[124:125]
	v_pk_mul_f32 v[62:63], v[62:63], v[126:127]
	v_pk_mul_f32 v[32:33], v[32:33], v[112:113]
	v_pk_mul_f32 v[34:35], v[34:35], v[114:115]
	v_pk_mul_f32 v[36:37], v[36:37], v[116:117]
	v_pk_mul_f32 v[38:39], v[38:39], v[118:119]
	v_pk_mul_f32 v[40:41], v[40:41], v[120:121]
	v_pk_mul_f32 v[42:43], v[42:43], v[122:123]
	v_pk_mul_f32 v[44:45], v[44:45], v[124:125]
	v_pk_mul_f32 v[46:47], v[46:47], v[126:127]
	v_pk_mul_f32 v[16:17], v[16:17], v[112:113]
	v_pk_mul_f32 v[18:19], v[18:19], v[114:115]
	v_pk_mul_f32 v[20:21], v[20:21], v[116:117]
	v_pk_mul_f32 v[22:23], v[22:23], v[118:119]
	v_pk_mul_f32 v[24:25], v[24:25], v[120:121]
	v_pk_mul_f32 v[26:27], v[26:27], v[122:123]
	v_pk_mul_f32 v[28:29], v[28:29], v[124:125]
	v_pk_mul_f32 v[30:31], v[30:31], v[126:127]
	v_mov_b32_dpp v128, v64 quad_perm:[1,0,3,2] row_mask:0xf bank_mask:0xf
	v_mov_b32_dpp v129, v65 quad_perm:[1,0,3,2] row_mask:0xf bank_mask:0xf
	v_mov_b32_dpp v130, v66 quad_perm:[1,0,3,2] row_mask:0xf bank_mask:0xf
	v_mov_b32_dpp v131, v67 quad_perm:[1,0,3,2] row_mask:0xf bank_mask:0xf
	v_mov_b32_dpp v132, v68 quad_perm:[1,0,3,2] row_mask:0xf bank_mask:0xf
	v_mov_b32_dpp v133, v69 quad_perm:[1,0,3,2] row_mask:0xf bank_mask:0xf
	v_mov_b32_dpp v134, v70 quad_perm:[1,0,3,2] row_mask:0xf bank_mask:0xf
	v_mov_b32_dpp v135, v71 quad_perm:[1,0,3,2] row_mask:0xf bank_mask:0xf
	v_mov_b32_dpp v136, v72 quad_perm:[1,0,3,2] row_mask:0xf bank_mask:0xf
	v_mov_b32_dpp v137, v73 quad_perm:[1,0,3,2] row_mask:0xf bank_mask:0xf
	v_mov_b32_dpp v138, v74 quad_perm:[1,0,3,2] row_mask:0xf bank_mask:0xf
	v_mov_b32_dpp v139, v75 quad_perm:[1,0,3,2] row_mask:0xf bank_mask:0xf
	v_mov_b32_dpp v140, v76 quad_perm:[1,0,3,2] row_mask:0xf bank_mask:0xf
	v_mov_b32_dpp v141, v77 quad_perm:[1,0,3,2] row_mask:0xf bank_mask:0xf
	v_mov_b32_dpp v142, v78 quad_perm:[1,0,3,2] row_mask:0xf bank_mask:0xf
	v_mov_b32_dpp v143, v79 quad_perm:[1,0,3,2] row_mask:0xf bank_mask:0xf
	v_cvt_pk_bf16_f32 v64, v64, v128
	v_cvt_pk_bf16_f32 v65, v65, v129
	v_cvt_pk_bf16_f32 v66, v66, v130
	v_cvt_pk_bf16_f32 v67, v67, v131
	v_cvt_pk_bf16_f32 v68, v68, v132
	v_cvt_pk_bf16_f32 v69, v69, v133
	v_cvt_pk_bf16_f32 v70, v70, v134
	v_cvt_pk_bf16_f32 v71, v71, v135
	v_cvt_pk_bf16_f32 v72, v72, v136
	v_cvt_pk_bf16_f32 v73, v73, v137
	v_cvt_pk_bf16_f32 v74, v74, v138
	v_cvt_pk_bf16_f32 v75, v75, v139
	v_cvt_pk_bf16_f32 v76, v76, v140
	v_cvt_pk_bf16_f32 v77, v77, v141
	v_cvt_pk_bf16_f32 v78, v78, v142
	v_cvt_pk_bf16_f32 v79, v79, v143
	v_mov_b32_dpp v128, v48 quad_perm:[1,0,3,2] row_mask:0xf bank_mask:0xf
	v_mov_b32_dpp v129, v49 quad_perm:[1,0,3,2] row_mask:0xf bank_mask:0xf
	v_mov_b32_dpp v130, v50 quad_perm:[1,0,3,2] row_mask:0xf bank_mask:0xf
	v_mov_b32_dpp v131, v51 quad_perm:[1,0,3,2] row_mask:0xf bank_mask:0xf
	v_mov_b32_dpp v132, v52 quad_perm:[1,0,3,2] row_mask:0xf bank_mask:0xf
	v_mov_b32_dpp v133, v53 quad_perm:[1,0,3,2] row_mask:0xf bank_mask:0xf
	v_mov_b32_dpp v134, v54 quad_perm:[1,0,3,2] row_mask:0xf bank_mask:0xf
	v_mov_b32_dpp v135, v55 quad_perm:[1,0,3,2] row_mask:0xf bank_mask:0xf
	v_mov_b32_dpp v136, v56 quad_perm:[1,0,3,2] row_mask:0xf bank_mask:0xf
	v_mov_b32_dpp v137, v57 quad_perm:[1,0,3,2] row_mask:0xf bank_mask:0xf
	v_mov_b32_dpp v138, v58 quad_perm:[1,0,3,2] row_mask:0xf bank_mask:0xf
	v_mov_b32_dpp v139, v59 quad_perm:[1,0,3,2] row_mask:0xf bank_mask:0xf
	v_mov_b32_dpp v140, v60 quad_perm:[1,0,3,2] row_mask:0xf bank_mask:0xf
	v_mov_b32_dpp v141, v61 quad_perm:[1,0,3,2] row_mask:0xf bank_mask:0xf
	v_mov_b32_dpp v142, v62 quad_perm:[1,0,3,2] row_mask:0xf bank_mask:0xf
	v_mov_b32_dpp v143, v63 quad_perm:[1,0,3,2] row_mask:0xf bank_mask:0xf
	v_cvt_pk_bf16_f32 v48, v48, v128
	v_cvt_pk_bf16_f32 v49, v49, v129
	v_cvt_pk_bf16_f32 v50, v50, v130
; __device__ __forceinline__ unsigned cvtpk(float lo, float hi) { const cvt_f32x2 v = {lo, hi}; const cvt_bf16x2 r = __builtin_convertvector(v, cvt_bf16x2); return __builtin_bit_cast(unsigned, r); }
; __device__ __forceinline__ int crow(int r, int hi) { return (r & 3) + 8 * (r >> 2) + 4 * hi; }
; template <int MODE, int VARI>
; __device__ __forceinline__ void attn_unit(LAS unsigned char* lds, const int tid, const AttnP& a, float c2, float lam, const float* subln, float outscale, float fox_u, const bool fast) {
;     ...
;     if (WIDE || wid < 4) {
;         bf16_t* Ow = a.O + (size_t)qpos0 * 2048;
; #pragma unroll
;         for (int r = 0; r < 16; ++r) { const int orow = crow(r, hi);
; #pragma unroll
;             for (int d = 0; d < 4; ++d) { const float v = o[d][r]; const float vn = __shfl_xor(v, 1);
;                 if ((r32 & 1) == 0) *(unsigned*)(Ow + (size_t)orow * 2048 + d * 32 + r32) = cvtpk(v, vn); } }
;     }
	v_cvt_pk_bf16_f32 v51, v51, v131
	v_cvt_pk_bf16_f32 v52, v52, v132
	v_cvt_pk_bf16_f32 v53, v53, v133
	v_cvt_pk_bf16_f32 v54, v54, v134
	v_cvt_pk_bf16_f32 v55, v55, v135
	v_cvt_pk_bf16_f32 v56, v56, v136
	v_cvt_pk_bf16_f32 v57, v57, v137
	v_cvt_pk_bf16_f32 v58, v58, v138
	v_cvt_pk_bf16_f32 v59, v59, v139
	v_cvt_pk_bf16_f32 v60, v60, v140
	v_cvt_pk_bf16_f32 v61, v61, v141
	v_cvt_pk_bf16_f32 v62, v62, v142
	v_cvt_pk_bf16_f32 v63, v63, v143
	v_mov_b32_dpp v128, v32 quad_perm:[1,0,3,2] row_mask:0xf bank_mask:0xf
	v_mov_b32_dpp v129, v33 quad_perm:[1,0,3,2] row_mask:0xf bank_mask:0xf
	v_mov_b32_dpp v130, v34 quad_perm:[1,0,3,2] row_mask:0xf bank_mask:0xf
	v_mov_b32_dpp v131, v35 quad_perm:[1,0,3,2] row_mask:0xf bank_mask:0xf
	v_mov_b32_dpp v132, v36 quad_perm:[1,0,3,2] row_mask:0xf bank_mask:0xf
	v_mov_b32_dpp v133, v37 quad_perm:[1,0,3,2] row_mask:0xf bank_mask:0xf
	v_mov_b32_dpp v134, v38 quad_perm:[1,0,3,2] row_mask:0xf bank_mask:0xf
	v_mov_b32_dpp v135, v39 quad_perm:[1,0,3,2] row_mask:0xf bank_mask:0xf
	v_mov_b32_dpp v136, v40 quad_perm:[1,0,3,2] row_mask:0xf bank_mask:0xf
	v_mov_b32_dpp v137, v41 quad_perm:[1,0,3,2] row_mask:0xf bank_mask:0xf
	v_mov_b32_dpp v138, v42 quad_perm:[1,0,3,2] row_mask:0xf bank_mask:0xf
	v_mov_b32_dpp v139, v43 quad_perm:[1,0,3,2] row_mask:0xf bank_mask:0xf
	v_mov_b32_dpp v140, v44 quad_perm:[1,0,3,2] row_mask:0xf bank_mask:0xf
	v_mov_b32_dpp v141, v45 quad_perm:[1,0,3,2] row_mask:0xf bank_mask:0xf
	v_mov_b32_dpp v142, v46 quad_perm:[1,0,3,2] row_mask:0xf bank_mask:0xf
	v_mov_b32_dpp v143, v47 quad_perm:[1,0,3,2] row_mask:0xf bank_mask:0xf
	v_cvt_pk_bf16_f32 v32, v32, v128
	v_cvt_pk_bf16_f32 v33, v33, v129
	v_cvt_pk_bf16_f32 v34, v34, v130
	v_cvt_pk_bf16_f32 v35, v35, v131
	v_cvt_pk_bf16_f32 v36, v36, v132
	v_cvt_pk_bf16_f32 v37, v37, v133
	v_cvt_pk_bf16_f32 v38, v38, v134
	v_cvt_pk_bf16_f32 v39, v39, v135
	v_cvt_pk_bf16_f32 v40, v40, v136
	v_cvt_pk_bf16_f32 v41, v41, v137
	v_cvt_pk_bf16_f32 v42, v42, v138
	v_cvt_pk_bf16_f32 v43, v43, v139
	v_cvt_pk_bf16_f32 v44, v44, v140
	v_cvt_pk_bf16_f32 v45, v45, v141
	v_cvt_pk_bf16_f32 v46, v46, v142
	v_cvt_pk_bf16_f32 v47, v47, v143
	v_mov_b32_dpp v128, v16 quad_perm:[1,0,3,2] row_mask:0xf bank_mask:0xf
	v_mov_b32_dpp v129, v17 quad_perm:[1,0,3,2] row_mask:0xf bank_mask:0xf
	v_mov_b32_dpp v130, v18 quad_perm:[1,0,3,2] row_mask:0xf bank_mask:0xf
	v_mov_b32_dpp v131, v19 quad_perm:[1,0,3,2] row_mask:0xf bank_mask:0xf
	v_mov_b32_dpp v132, v20 quad_perm:[1,0,3,2] row_mask:0xf bank_mask:0xf
	v_mov_b32_dpp v133, v21 quad_perm:[1,0,3,2] row_mask:0xf bank_mask:0xf
	v_mov_b32_dpp v134, v22 quad_perm:[1,0,3,2] row_mask:0xf bank_mask:0xf
	v_mov_b32_dpp v135, v23 quad_perm:[1,0,3,2] row_mask:0xf bank_mask:0xf
	v_mov_b32_dpp v136, v24 quad_perm:[1,0,3,2] row_mask:0xf bank_mask:0xf
	v_mov_b32_dpp v137, v25 quad_perm:[1,0,3,2] row_mask:0xf bank_mask:0xf
	v_mov_b32_dpp v138, v26 quad_perm:[1,0,3,2] row_mask:0xf bank_mask:0xf
	v_mov_b32_dpp v139, v27 quad_perm:[1,0,3,2] row_mask:0xf bank_mask:0xf
	v_mov_b32_dpp v140, v28 quad_perm:[1,0,3,2] row_mask:0xf bank_mask:0xf
	v_mov_b32_dpp v141, v29 quad_perm:[1,0,3,2] row_mask:0xf bank_mask:0xf
	v_mov_b32_dpp v142, v30 quad_perm:[1,0,3,2] row_mask:0xf bank_mask:0xf
	v_mov_b32_dpp v143, v31 quad_perm:[1,0,3,2] row_mask:0xf bank_mask:0xf
	v_cvt_pk_bf16_f32 v16, v16, v128
	v_cvt_pk_bf16_f32 v17, v17, v129
	v_cvt_pk_bf16_f32 v18, v18, v130
	v_cvt_pk_bf16_f32 v19, v19, v131
	v_cvt_pk_bf16_f32 v20, v20, v132
	v_cvt_pk_bf16_f32 v21, v21, v133
	v_cvt_pk_bf16_f32 v22, v22, v134
	v_cvt_pk_bf16_f32 v23, v23, v135
	v_cvt_pk_bf16_f32 v24, v24, v136
	v_cvt_pk_bf16_f32 v25, v25, v137
	v_cvt_pk_bf16_f32 v26, v26, v138
; __device__ __forceinline__ unsigned cvtpk(float lo, float hi) { const cvt_f32x2 v = {lo, hi}; const cvt_bf16x2 r = __builtin_convertvector(v, cvt_bf16x2); return __builtin_bit_cast(unsigned, r); }
; __device__ __forceinline__ int crow(int r, int hi) { return (r & 3) + 8 * (r >> 2) + 4 * hi; }
; template <int MODE, int VARI>
; __device__ __forceinline__ void attn_unit(LAS unsigned char* lds, const int tid, const AttnP& a, float c2, float lam, const float* subln, float outscale, float fox_u, const bool fast) {
;     ...
;     if (WIDE || wid < 4) {
;         bf16_t* Ow = a.O + (size_t)qpos0 * 2048;
; #pragma unroll
;         for (int r = 0; r < 16; ++r) { const int orow = crow(r, hi);
; #pragma unroll
;             for (int d = 0; d < 4; ++d) { const float v = o[d][r]; const float vn = __shfl_xor(v, 1);
;                 if ((r32 & 1) == 0) *(unsigned*)(Ow + (size_t)orow * 2048 + d * 32 + r32) = cvtpk(v, vn); } }
;     }
	v_cvt_pk_bf16_f32 v27, v27, v139
	v_cvt_pk_bf16_f32 v28, v28, v140
	v_cvt_pk_bf16_f32 v29, v29, v141
	v_cvt_pk_bf16_f32 v30, v30, v142
	v_cvt_pk_bf16_f32 v31, v31, v143
	v_mov_b32_e32 v112, v14
	v_add_u32_e32 v113, 0x1000, v14
	v_add_u32_e32 v114, 0x2000, v14
	v_add_u32_e32 v115, 0x3000, v14
	v_add_u32_e32 v116, 0x8000, v14
	v_add_u32_e32 v117, 0x9000, v14
	v_add_u32_e32 v118, 0xa000, v14
	v_add_u32_e32 v119, 0xb000, v14
	v_add_u32_e32 v120, 0x10000, v14
	v_add_u32_e32 v121, 0x11000, v14
	v_add_u32_e32 v122, 0x12000, v14
	v_add_u32_e32 v123, 0x13000, v14
	v_add_u32_e32 v124, 0x18000, v14
	v_add_u32_e32 v125, 0x19000, v14
	v_add_u32_e32 v126, 0x1a000, v14
	v_add_u32_e32 v127, 0x1b000, v14
	s_and_saveexec_b64 s[14:15], s[12:13]
	global_store_dword v112, v64, s[6:7]
	global_store_dword v112, v48, s[6:7] offset:64
	global_store_dword v112, v32, s[6:7] offset:128
	global_store_dword v112, v16, s[6:7] offset:192
	global_store_dword v113, v65, s[6:7]
	global_store_dword v113, v49, s[6:7] offset:64
	global_store_dword v113, v33, s[6:7] offset:128
	global_store_dword v113, v17, s[6:7] offset:192
	global_store_dword v114, v66, s[6:7]
	global_store_dword v114, v50, s[6:7] offset:64
	global_store_dword v114, v34, s[6:7] offset:128
	global_store_dword v114, v18, s[6:7] offset:192
	global_store_dword v115, v67, s[6:7]
	global_store_dword v115, v51, s[6:7] offset:64
	global_store_dword v115, v35, s[6:7] offset:128
	global_store_dword v115, v19, s[6:7] offset:192
	global_store_dword v116, v68, s[6:7]
	global_store_dword v116, v52, s[6:7] offset:64
	global_store_dword v116, v36, s[6:7] offset:128
	global_store_dword v116, v20, s[6:7] offset:192
	global_store_dword v117, v69, s[6:7]
	global_store_dword v117, v53, s[6:7] offset:64
	global_store_dword v117, v37, s[6:7] offset:128
	global_store_dword v117, v21, s[6:7] offset:192
	global_store_dword v118, v70, s[6:7]
	global_store_dword v118, v54, s[6:7] offset:64
	global_store_dword v118, v38, s[6:7] offset:128
	global_store_dword v118, v22, s[6:7] offset:192
	global_store_dword v119, v71, s[6:7]
	global_store_dword v119, v55, s[6:7] offset:64
	global_store_dword v119, v39, s[6:7] offset:128
	global_store_dword v119, v23, s[6:7] offset:192
	global_store_dword v120, v72, s[6:7]
	global_store_dword v120, v56, s[6:7] offset:64
	global_store_dword v120, v40, s[6:7] offset:128
	global_store_dword v120, v24, s[6:7] offset:192
	global_store_dword v121, v73, s[6:7]
	global_store_dword v121, v57, s[6:7] offset:64
	global_store_dword v121, v41, s[6:7] offset:128
	global_store_dword v121, v25, s[6:7] offset:192
	global_store_dword v122, v74, s[6:7]
	global_store_dword v122, v58, s[6:7] offset:64
	global_store_dword v122, v42, s[6:7] offset:128
	global_store_dword v122, v26, s[6:7] offset:192
	global_store_dword v123, v75, s[6:7]
	global_store_dword v123, v59, s[6:7] offset:64
	global_store_dword v123, v43, s[6:7] offset:128
	global_store_dword v123, v27, s[6:7] offset:192
	global_store_dword v124, v76, s[6:7]
	global_store_dword v124, v60, s[6:7] offset:64
	global_store_dword v124, v44, s[6:7] offset:128
	global_store_dword v124, v28, s[6:7] offset:192
	global_store_dword v125, v77, s[6:7]
	global_store_dword v125, v61, s[6:7] offset:64
	global_store_dword v125, v45, s[6:7] offset:128
	global_store_dword v125, v29, s[6:7] offset:192
	global_store_dword v126, v78, s[6:7]
	global_store_dword v126, v62, s[6:7] offset:64
	global_store_dword v126, v46, s[6:7] offset:128
	global_store_dword v126, v30, s[6:7] offset:192
	global_store_dword v127, v79, s[6:7]
	global_store_dword v127, v63, s[6:7] offset:64
	global_store_dword v127, v47, s[6:7] offset:128
	global_store_dword v127, v31, s[6:7] offset:192
